# bf16 packs via v_cvt_pk_bf16_f32 in attention (P/O/Q/K) and spatial gating (LN + gated output), MFMA/readlane distances re-padded after the deletions; seams + prologue edits kept
# baseline (speedup 1.0000x reference)
; #define LAS __attribute__((address_space(3)))
; __device__ __forceinline__ unsigned pk2(float lo, float hi) { return f2bf(lo) | (f2bf(hi) << 16); }
; __device__ __forceinline__ float bflo(unsigned w) { return __uint_as_float(w << 16); }
; __device__ __forceinline__ float bfhi(unsigned w) { return __uint_as_float(w & 0xffff0000u); }
; __device__ __forceinline__ void spatial_phase(LAS unsigned char* lds, const bf16* Z, bf16* GT, const float* vstat, const float* lng, const float* lnb, const float* wsp, const float* bsp) {
;     ...
;         for (int j = 0; j < 8; ++j) { const int sr = (tid >> 5) + 16 * j; const u32x4 w = vw[j]; const float mu = MU[sr], rs = RS[sr];
;             f32x4 v0 = (f32x4){bflo(w.x), bfhi(w.x), bflo(w.y), bfhi(w.y)}, v1 = (f32x4){bflo(w.z), bfhi(w.z), bflo(w.w), bfhi(w.w)};
;             v0 = (v0 - mu) * rs * g0 + b0; v1 = (v1 - mu) * rs * g1 + b1;
;             u32x4 o; o.x = pk2(v0[0], v0[1]); o.y = pk2(v0[2], v0[3]); o.z = pk2(v1[0], v1[1]); o.w = pk2(v1[2], v1[3]); *(LAS u32x4*)(Vl + sr * VP + c8) = o; }
.LBB0_760:
	s_or_b64 exec, exec, s[0:1]
	s_waitcnt lgkmcnt(0)
	s_barrier
	ds_read_b32 v49, v133
	ds_read_b32 v48, v134
	s_waitcnt vmcnt(7)
	v_lshlrev_b32_e32 v50, 16, v44
	v_and_b32_e32 v51, 0xffff0000, v44
	v_lshlrev_b32_e32 v44, 16, v45
	v_and_b32_e32 v45, 0xffff0000, v45
	v_lshlrev_b32_e32 v52, 16, v46
	v_and_b32_e32 v53, 0xffff0000, v46
	v_lshlrev_b32_e32 v54, 16, v47
	v_and_b32_e32 v55, 0xffff0000, v47
	s_waitcnt lgkmcnt(1)
	v_sub_f32_e32 v45, v45, v49
	v_sub_f32_e32 v44, v44, v49
	v_sub_f32_e32 v47, v51, v49
	v_sub_f32_e32 v46, v50, v49
	s_waitcnt lgkmcnt(0)
	v_pk_mul_f32 v[46:47], v[48:49], v[46:47] op_sel_hi:[0,1]
	v_pk_mul_f32 v[44:45], v[48:49], v[44:45] op_sel_hi:[0,1]
	v_pk_fma_f32 v[50:51], v[2:3], v[44:45], v[14:15]
	v_pk_fma_f32 v[44:45], v[0:1], v[46:47], v[12:13]
	v_sub_f32_e32 v47, v55, v49
	v_sub_f32_e32 v46, v54, v49
	v_sub_f32_e32 v53, v53, v49
	v_sub_f32_e32 v52, v52, v49
	v_pk_mul_f32 v[52:53], v[48:49], v[52:53] op_sel_hi:[0,1]
	v_pk_mul_f32 v[46:47], v[48:49], v[46:47] op_sel_hi:[0,1]
	v_pk_fma_f32 v[48:49], v[6:7], v[46:47], v[10:11]
	v_pk_fma_f32 v[46:47], v[4:5], v[52:53], v[8:9]
	v_cvt_pk_bf16_f32 v44, v44, v45
	v_cvt_pk_bf16_f32 v45, v50, v51
	v_cvt_pk_bf16_f32 v46, v46, v47
	v_cvt_pk_bf16_f32 v47, v48, v49
	ds_write_b128 v156, v[44:47] offset:34816
	ds_read_b32 v45, v135
	ds_read_b32 v44, v136
	s_waitcnt vmcnt(6)
	v_lshlrev_b32_e32 v46, 16, v40
	v_and_b32_e32 v47, 0xffff0000, v40
	v_lshlrev_b32_e32 v40, 16, v41
	v_and_b32_e32 v41, 0xffff0000, v41
	v_lshlrev_b32_e32 v48, 16, v42
	v_and_b32_e32 v49, 0xffff0000, v42
	v_lshlrev_b32_e32 v50, 16, v43
	v_and_b32_e32 v51, 0xffff0000, v43
	s_waitcnt lgkmcnt(1)
	v_sub_f32_e32 v41, v41, v45
	v_sub_f32_e32 v40, v40, v45
	v_sub_f32_e32 v43, v47, v45
	v_sub_f32_e32 v42, v46, v45
	s_waitcnt lgkmcnt(0)
	v_pk_mul_f32 v[42:43], v[44:45], v[42:43] op_sel_hi:[0,1]
	v_pk_mul_f32 v[40:41], v[44:45], v[40:41] op_sel_hi:[0,1]
	v_pk_fma_f32 v[46:47], v[2:3], v[40:41], v[14:15]
	v_pk_fma_f32 v[40:41], v[0:1], v[42:43], v[12:13]
	v_sub_f32_e32 v43, v51, v45
	v_sub_f32_e32 v42, v50, v45
	v_sub_f32_e32 v49, v49, v45
	v_sub_f32_e32 v48, v48, v45
	v_pk_mul_f32 v[48:49], v[44:45], v[48:49] op_sel_hi:[0,1]
	v_pk_mul_f32 v[42:43], v[44:45], v[42:43] op_sel_hi:[0,1]
	v_pk_fma_f32 v[44:45], v[6:7], v[42:43], v[10:11]
	v_pk_fma_f32 v[42:43], v[4:5], v[48:49], v[8:9]
	v_cvt_pk_bf16_f32 v40, v40, v41
	v_cvt_pk_bf16_f32 v41, v46, v47
	v_cvt_pk_bf16_f32 v42, v42, v43
	v_cvt_pk_bf16_f32 v43, v44, v45
	ds_write_b128 v156, v[40:43] offset:43520
	ds_read_b32 v41, v137
	ds_read_b32 v40, v138
	s_waitcnt vmcnt(5)
	v_lshlrev_b32_e32 v42, 16, v36
	v_and_b32_e32 v43, 0xffff0000, v36
	v_lshlrev_b32_e32 v36, 16, v37
	v_and_b32_e32 v37, 0xffff0000, v37
	v_lshlrev_b32_e32 v44, 16, v38
	v_and_b32_e32 v45, 0xffff0000, v38
	v_lshlrev_b32_e32 v46, 16, v39
	v_and_b32_e32 v47, 0xffff0000, v39
	s_waitcnt lgkmcnt(1)
	v_sub_f32_e32 v37, v37, v41
	v_sub_f32_e32 v36, v36, v41
	v_sub_f32_e32 v39, v43, v41
	v_sub_f32_e32 v38, v42, v41
	s_waitcnt lgkmcnt(0)
	v_pk_mul_f32 v[38:39], v[40:41], v[38:39] op_sel_hi:[0,1]
	v_pk_mul_f32 v[36:37], v[40:41], v[36:37] op_sel_hi:[0,1]
	v_pk_fma_f32 v[42:43], v[2:3], v[36:37], v[14:15]
	v_pk_fma_f32 v[36:37], v[0:1], v[38:39], v[12:13]
	v_sub_f32_e32 v39, v47, v41
	v_sub_f32_e32 v38, v46, v41
	v_sub_f32_e32 v45, v45, v41
	v_sub_f32_e32 v44, v44, v41
	v_pk_mul_f32 v[44:45], v[40:41], v[44:45] op_sel_hi:[0,1]
	v_pk_mul_f32 v[38:39], v[40:41], v[38:39] op_sel_hi:[0,1]
	v_pk_fma_f32 v[40:41], v[6:7], v[38:39], v[10:11]
	v_pk_fma_f32 v[38:39], v[4:5], v[44:45], v[8:9]
	v_cvt_pk_bf16_f32 v36, v36, v37
	v_cvt_pk_bf16_f32 v37, v42, v43
	v_cvt_pk_bf16_f32 v38, v38, v39
	v_cvt_pk_bf16_f32 v39, v40, v41
	ds_write_b128 v156, v[36:39] offset:52224
	ds_read_b32 v37, v139
	ds_read_b32 v36, v140
	s_waitcnt vmcnt(4)
	v_lshlrev_b32_e32 v38, 16, v32
	v_and_b32_e32 v39, 0xffff0000, v32
	v_lshlrev_b32_e32 v32, 16, v33
	v_and_b32_e32 v33, 0xffff0000, v33
	v_lshlrev_b32_e32 v40, 16, v34
	v_and_b32_e32 v41, 0xffff0000, v34
	v_lshlrev_b32_e32 v42, 16, v35
	v_and_b32_e32 v43, 0xffff0000, v35
	s_waitcnt lgkmcnt(1)
	v_sub_f32_e32 v33, v33, v37
	v_sub_f32_e32 v32, v32, v37
	v_sub_f32_e32 v35, v39, v37
	v_sub_f32_e32 v34, v38, v37
	s_waitcnt lgkmcnt(0)
	v_pk_mul_f32 v[34:35], v[36:37], v[34:35] op_sel_hi:[0,1]
	v_pk_mul_f32 v[32:33], v[36:37], v[32:33] op_sel_hi:[0,1]
	v_pk_fma_f32 v[38:39], v[2:3], v[32:33], v[14:15]
	v_pk_fma_f32 v[32:33], v[0:1], v[34:35], v[12:13]
	v_sub_f32_e32 v35, v43, v37
	v_sub_f32_e32 v34, v42, v37
	v_sub_f32_e32 v41, v41, v37
	v_sub_f32_e32 v40, v40, v37
	v_pk_mul_f32 v[40:41], v[36:37], v[40:41] op_sel_hi:[0,1]
	v_pk_mul_f32 v[34:35], v[36:37], v[34:35] op_sel_hi:[0,1]
	v_pk_fma_f32 v[36:37], v[6:7], v[34:35], v[10:11]
	v_pk_fma_f32 v[34:35], v[4:5], v[40:41], v[8:9]
	v_cvt_pk_bf16_f32 v32, v32, v33
	v_cvt_pk_bf16_f32 v33, v38, v39
	v_cvt_pk_bf16_f32 v34, v34, v35
	v_cvt_pk_bf16_f32 v35, v36, v37
	ds_write_b128 v156, v[32:35] offset:60928
	ds_read_b32 v33, v141
	ds_read_b32 v32, v142
	s_waitcnt vmcnt(3)
	v_lshlrev_b32_e32 v34, 16, v28
	v_and_b32_e32 v35, 0xffff0000, v28
	v_lshlrev_b32_e32 v28, 16, v29
	v_and_b32_e32 v29, 0xffff0000, v29
	v_lshlrev_b32_e32 v36, 16, v30
	v_and_b32_e32 v37, 0xffff0000, v30
	v_lshlrev_b32_e32 v38, 16, v31
	v_and_b32_e32 v39, 0xffff0000, v31
	s_waitcnt lgkmcnt(1)
	v_sub_f32_e32 v29, v29, v33
	v_sub_f32_e32 v28, v28, v33
	v_sub_f32_e32 v31, v35, v33
	v_sub_f32_e32 v30, v34, v33
	s_waitcnt lgkmcnt(0)
; #define LAS __attribute__((address_space(3)))
; __device__ __forceinline__ unsigned pk2(float lo, float hi) { return f2bf(lo) | (f2bf(hi) << 16); }
; __device__ __forceinline__ float bflo(unsigned w) { return __uint_as_float(w << 16); }
; __device__ __forceinline__ float bfhi(unsigned w) { return __uint_as_float(w & 0xffff0000u); }
; __device__ __forceinline__ void spatial_phase(LAS unsigned char* lds, const bf16* Z, bf16* GT, const float* vstat, const float* lng, const float* lnb, const float* wsp, const float* bsp) {
;     ...
;         for (int j = 0; j < 8; ++j) { const int sr = (tid >> 5) + 16 * j; const u32x4 w = vw[j]; const float mu = MU[sr], rs = RS[sr];
;             f32x4 v0 = (f32x4){bflo(w.x), bfhi(w.x), bflo(w.y), bfhi(w.y)}, v1 = (f32x4){bflo(w.z), bfhi(w.z), bflo(w.w), bfhi(w.w)};
;             v0 = (v0 - mu) * rs * g0 + b0; v1 = (v1 - mu) * rs * g1 + b1;
;             u32x4 o; o.x = pk2(v0[0], v0[1]); o.y = pk2(v0[2], v0[3]); o.z = pk2(v1[0], v1[1]); o.w = pk2(v1[2], v1[3]); *(LAS u32x4*)(Vl + sr * VP + c8) = o; }
;         u32x2 uw[4][4];
; #pragma unroll
;         for (int tt = 0; tt < 4; ++tt)
; #pragma unroll
;             for (int ct = 0; ct < 4; ++ct) uw[tt][ct] = *(const u32x2*)(Z + zpan + (size_t)g * 65536 + (size_t)(zrow + th * 64 + tt * 16 + fr) * 256 + cq * 64 + ct * 16 + 4 * fq);
;         __syncthreads();
	v_pk_mul_f32 v[30:31], v[32:33], v[30:31] op_sel_hi:[0,1]
	v_pk_mul_f32 v[28:29], v[32:33], v[28:29] op_sel_hi:[0,1]
	v_pk_fma_f32 v[34:35], v[2:3], v[28:29], v[14:15]
	v_pk_fma_f32 v[28:29], v[0:1], v[30:31], v[12:13]
	v_sub_f32_e32 v31, v39, v33
	v_sub_f32_e32 v30, v38, v33
	v_sub_f32_e32 v37, v37, v33
	v_sub_f32_e32 v36, v36, v33
	v_pk_mul_f32 v[36:37], v[32:33], v[36:37] op_sel_hi:[0,1]
	v_pk_mul_f32 v[30:31], v[32:33], v[30:31] op_sel_hi:[0,1]
	v_pk_fma_f32 v[32:33], v[6:7], v[30:31], v[10:11]
	v_pk_fma_f32 v[30:31], v[4:5], v[36:37], v[8:9]
	v_cvt_pk_bf16_f32 v28, v28, v29
	v_cvt_pk_bf16_f32 v29, v34, v35
	v_cvt_pk_bf16_f32 v30, v30, v31
	v_cvt_pk_bf16_f32 v31, v32, v33
	ds_write_b128 v157, v[28:31] offset:34816
	ds_read_b32 v29, v143
	ds_read_b32 v28, v144
	s_waitcnt vmcnt(2)
	v_lshlrev_b32_e32 v30, 16, v24
	v_and_b32_e32 v31, 0xffff0000, v24
	v_lshlrev_b32_e32 v24, 16, v25
	v_and_b32_e32 v25, 0xffff0000, v25
	v_lshlrev_b32_e32 v32, 16, v26
	v_and_b32_e32 v33, 0xffff0000, v26
	v_lshlrev_b32_e32 v34, 16, v27
	v_and_b32_e32 v35, 0xffff0000, v27
	s_waitcnt lgkmcnt(1)
	v_sub_f32_e32 v25, v25, v29
	v_sub_f32_e32 v24, v24, v29
	v_sub_f32_e32 v27, v31, v29
	v_sub_f32_e32 v26, v30, v29
	s_waitcnt lgkmcnt(0)
	v_pk_mul_f32 v[26:27], v[28:29], v[26:27] op_sel_hi:[0,1]
	v_pk_mul_f32 v[24:25], v[28:29], v[24:25] op_sel_hi:[0,1]
	v_pk_fma_f32 v[30:31], v[2:3], v[24:25], v[14:15]
	v_pk_fma_f32 v[24:25], v[0:1], v[26:27], v[12:13]
	v_sub_f32_e32 v27, v35, v29
	v_sub_f32_e32 v26, v34, v29
	v_sub_f32_e32 v33, v33, v29
	v_sub_f32_e32 v32, v32, v29
	v_pk_mul_f32 v[32:33], v[28:29], v[32:33] op_sel_hi:[0,1]
	v_pk_mul_f32 v[26:27], v[28:29], v[26:27] op_sel_hi:[0,1]
	v_pk_fma_f32 v[28:29], v[6:7], v[26:27], v[10:11]
	v_pk_fma_f32 v[26:27], v[4:5], v[32:33], v[8:9]
	v_cvt_pk_bf16_f32 v24, v24, v25
	v_cvt_pk_bf16_f32 v25, v30, v31
	v_cvt_pk_bf16_f32 v26, v26, v27
	v_cvt_pk_bf16_f32 v27, v28, v29
	ds_write_b128 v157, v[24:27] offset:43520
	ds_read_b32 v25, v145
	ds_read_b32 v24, v146
	s_waitcnt vmcnt(1)
	v_lshlrev_b32_e32 v26, 16, v20
	v_and_b32_e32 v27, 0xffff0000, v20
	v_lshlrev_b32_e32 v20, 16, v21
	v_and_b32_e32 v21, 0xffff0000, v21
	v_lshlrev_b32_e32 v28, 16, v22
	v_and_b32_e32 v29, 0xffff0000, v22
	v_lshlrev_b32_e32 v30, 16, v23
	v_and_b32_e32 v31, 0xffff0000, v23
	s_waitcnt lgkmcnt(1)
	v_sub_f32_e32 v21, v21, v25
	v_sub_f32_e32 v20, v20, v25
	v_sub_f32_e32 v23, v27, v25
	v_sub_f32_e32 v22, v26, v25
	s_waitcnt lgkmcnt(0)
	v_pk_mul_f32 v[22:23], v[24:25], v[22:23] op_sel_hi:[0,1]
	v_pk_mul_f32 v[20:21], v[24:25], v[20:21] op_sel_hi:[0,1]
	v_pk_fma_f32 v[26:27], v[2:3], v[20:21], v[14:15]
	v_pk_fma_f32 v[20:21], v[0:1], v[22:23], v[12:13]
	v_sub_f32_e32 v23, v31, v25
	v_sub_f32_e32 v22, v30, v25
	v_sub_f32_e32 v29, v29, v25
	v_sub_f32_e32 v28, v28, v25
	v_pk_mul_f32 v[28:29], v[24:25], v[28:29] op_sel_hi:[0,1]
	v_pk_mul_f32 v[22:23], v[24:25], v[22:23] op_sel_hi:[0,1]
	v_pk_fma_f32 v[24:25], v[6:7], v[22:23], v[10:11]
	v_pk_fma_f32 v[22:23], v[4:5], v[28:29], v[8:9]
	v_cvt_pk_bf16_f32 v20, v20, v21
	v_cvt_pk_bf16_f32 v21, v26, v27
	v_cvt_pk_bf16_f32 v22, v22, v23
	v_cvt_pk_bf16_f32 v23, v24, v25
	ds_write_b128 v157, v[20:23] offset:52224
	ds_read_b32 v21, v147
	ds_read_b32 v20, v148
	s_waitcnt vmcnt(0)
	v_lshlrev_b32_e32 v22, 16, v16
	v_and_b32_e32 v23, 0xffff0000, v16
	v_lshlrev_b32_e32 v16, 16, v17
	v_and_b32_e32 v17, 0xffff0000, v17
	v_lshlrev_b32_e32 v24, 16, v18
	v_and_b32_e32 v25, 0xffff0000, v18
	v_lshlrev_b32_e32 v26, 16, v19
	v_and_b32_e32 v27, 0xffff0000, v19
	s_waitcnt lgkmcnt(1)
	v_sub_f32_e32 v17, v17, v21
	v_sub_f32_e32 v16, v16, v21
	v_sub_f32_e32 v19, v23, v21
	v_sub_f32_e32 v18, v22, v21
	s_waitcnt lgkmcnt(0)
	v_pk_mul_f32 v[18:19], v[20:21], v[18:19] op_sel_hi:[0,1]
	v_pk_mul_f32 v[16:17], v[20:21], v[16:17] op_sel_hi:[0,1]
	v_pk_fma_f32 v[22:23], v[2:3], v[16:17], v[14:15]
	v_pk_fma_f32 v[16:17], v[0:1], v[18:19], v[12:13]
	v_sub_f32_e32 v19, v27, v21
	v_sub_f32_e32 v18, v26, v21
	v_sub_f32_e32 v25, v25, v21
	v_sub_f32_e32 v24, v24, v21
	v_pk_mul_f32 v[24:25], v[20:21], v[24:25] op_sel_hi:[0,1]
	v_pk_mul_f32 v[18:19], v[20:21], v[18:19] op_sel_hi:[0,1]
	v_pk_fma_f32 v[20:21], v[6:7], v[18:19], v[10:11]
	v_pk_fma_f32 v[18:19], v[4:5], v[24:25], v[8:9]
	v_cvt_pk_bf16_f32 v16, v16, v17
	v_cvt_pk_bf16_f32 v17, v22, v23
	v_cvt_pk_bf16_f32 v18, v18, v19
	s_mov_b32 s93, s81
	s_lshl_b64 s[0:1], s[92:93], 17
	s_add_u32 s0, s86, s0
	v_cvt_pk_bf16_f32 v19, v20, v21
	s_addc_u32 s1, s87, s1
	v_mov_b32_e32 v81, v59
	ds_write_b128 v157, v[16:19] offset:60928
	v_lshl_add_u64 v[16:17], s[0:1], 0, v[80:81]
	v_mov_b32_e32 v83, v59
	v_lshl_add_u64 v[16:17], v[16:17], 0, v[82:83]
	v_add_lshl_u32 v58, s94, v57, 9
	v_lshl_add_u64 v[122:123], v[16:17], 0, v[58:59]
	v_add_co_u32_e64 v110, s[72:73], s4, v122
	global_load_dwordx2 v[130:131], v[122:123], off
	global_load_dwordx2 v[128:129], v[122:123], off offset:32
	global_load_dwordx2 v[126:127], v[122:123], off offset:64
	global_load_dwordx2 v[124:125], v[122:123], off offset:96
	v_addc_co_u32_e64 v111, s[72:73], 0, v123, s[72:73]
	v_add_co_u32_e64 v100, s[72:73], s5, v122
	global_load_dwordx2 v[120:121], v[110:111], off
	global_load_dwordx2 v[118:119], v[110:111], off offset:32
	global_load_dwordx2 v[116:117], v[110:111], off offset:64
	global_load_dwordx2 v[114:115], v[110:111], off offset:96
	v_addc_co_u32_e64 v101, s[72:73], 0, v123, s[72:73]
	v_add_co_u32_e64 v92, s[72:73], s95, v122
	global_load_dwordx2 v[112:113], v[100:101], off
	global_load_dwordx2 v[108:109], v[100:101], off offset:32
	global_load_dwordx2 v[106:107], v[100:101], off offset:64
	global_load_dwordx2 v[104:105], v[100:101], off offset:96
	v_addc_co_u32_e64 v93, s[72:73], 0, v123, s[72:73]
	global_load_dwordx2 v[102:103], v[92:93], off
	global_load_dwordx2 v[98:99], v[92:93], off offset:32
	global_load_dwordx2 v[96:97], v[92:93], off offset:64
	global_load_dwordx2 v[94:95], v[92:93], off offset:96
	s_waitcnt lgkmcnt(0)
	s_barrier
; #define LAS __attribute__((address_space(3)))
; __device__ __forceinline__ s16x4 tr_read(const LAS bf16* p) { return __builtin_bit_cast(s16x4, __builtin_amdgcn_ds_read_tr16_b64_v4i16((LAS s16x4*)p)); }
; __device__ __forceinline__ void spatial_phase(LAS unsigned char* lds, const bf16* Z, bf16* GT, const float* vstat, const float* lng, const float* lnb, const float* wsp, const float* bsp) {
;     ...
; #pragma unroll
;         for (int ks = 0; ks < 4; ++ks) {
;             bf16x8 wf[4], vf[4];
; #pragma unroll
;             for (int tt = 0; tt < 4; ++tt) wf[tt] = *(const LAS bf16x8*)(Wl + (th * 64 + tt * 16 + fr) * WP + ks * 32 + fq * 8);
; #pragma unroll
;             for (int ct = 0; ct < 4; ++ct) { const LAS bf16* vp = Vl + (ks * 32 + 8 * fq + q4) * VP + cq * 64 + ct * 16 + 4 * p4;
;                 const s16x4 lo = tr_read(vp), hi = tr_read(vp + 4 * VP); vf[ct] = (bf16x8){lo[0], lo[1], lo[2], lo[3], hi[0], hi[1], hi[2], hi[3]}; }
; #pragma unroll
;             for (int ct = 0; ct < 4; ++ct)
; #pragma unroll
;                 for (int tt = 0; tt < 4; ++tt) acc[ct][tt] = __builtin_amdgcn_mfma_f32_16x16x32_bf16(vf[ct], wf[tt], acc[ct][tt], 0, 0, 0);
;         }
	ds_read_b64_tr_b16 v[18:19], v149 offset:36992
	ds_read_b64_tr_b16 v[16:17], v149 offset:34816
	ds_read_b128 v[20:23], v158
	ds_read_b128 v[28:31], v158 offset:4352
	ds_read_b128 v[36:39], v158 offset:8704
	ds_read_b128 v[44:47], v158 offset:13056
	ds_read_b64_tr_b16 v[48:49], v149 offset:34848
	ds_read_b64_tr_b16 v[50:51], v149 offset:37024
	ds_read_b64_tr_b16 v[168:169], v149 offset:34880
	ds_read_b64_tr_b16 v[170:171], v149 offset:37056
	ds_read_b64_tr_b16 v[184:185], v149 offset:34912
	ds_read_b64_tr_b16 v[186:187], v149 offset:37088
	s_waitcnt lgkmcnt(9)
	v_mfma_f32_16x16x32_bf16 v[24:27], v[16:19], v[20:23], 0
	ds_read_b64_tr_b16 v[188:189], v149 offset:52224
	ds_read_b64_tr_b16 v[190:191], v149 offset:54400
	ds_read_b128 v[192:195], v158 offset:4416
	ds_read_b128 v[196:199], v158 offset:8768
	s_waitcnt lgkmcnt(12)
	v_mfma_f32_16x16x32_bf16 v[32:35], v[16:19], v[28:31], 0
	s_waitcnt lgkmcnt(11)
	v_mfma_f32_16x16x32_bf16 v[40:43], v[16:19], v[36:39], 0
	s_waitcnt lgkmcnt(10)
	v_mfma_f32_16x16x32_bf16 v[16:19], v[16:19], v[44:47], 0
	s_waitcnt lgkmcnt(8)
	v_mfma_f32_16x16x32_bf16 v[52:55], v[48:51], v[20:23], 0
	v_mfma_f32_16x16x32_bf16 v[160:163], v[48:51], v[28:31], 0
	v_mfma_f32_16x16x32_bf16 v[164:167], v[48:51], v[36:39], 0
	v_mfma_f32_16x16x32_bf16 v[48:51], v[48:51], v[44:47], 0
	s_waitcnt lgkmcnt(6)
	v_mfma_f32_16x16x32_bf16 v[172:175], v[168:171], v[20:23], 0
	v_mfma_f32_16x16x32_bf16 v[176:179], v[168:171], v[28:31], 0
	v_mfma_f32_16x16x32_bf16 v[180:183], v[168:171], v[36:39], 0
	v_mfma_f32_16x16x32_bf16 v[168:171], v[168:171], v[44:47], 0
	s_waitcnt lgkmcnt(4)
	v_mfma_f32_16x16x32_bf16 v[20:23], v[184:187], v[20:23], 0
	v_mfma_f32_16x16x32_bf16 v[28:31], v[184:187], v[28:31], 0
	v_mfma_f32_16x16x32_bf16 v[36:39], v[184:187], v[36:39], 0
	v_mfma_f32_16x16x32_bf16 v[44:47], v[184:187], v[44:47], 0
	ds_read_b128 v[184:187], v158 offset:64
	ds_read_b128 v[202:205], v158 offset:13120
	ds_read_b64_tr_b16 v[206:207], v149 offset:52256
	ds_read_b64_tr_b16 v[208:209], v149 offset:54432
	s_waitcnt lgkmcnt(3)
	v_mfma_f32_16x16x32_bf16 v[24:27], v[188:191], v[184:187], v[24:27]
	v_mfma_f32_16x16x32_bf16 v[32:35], v[188:191], v[192:195], v[32:35]
	v_mfma_f32_16x16x32_bf16 v[40:43], v[188:191], v[196:199], v[40:43]
	s_waitcnt lgkmcnt(2)
	v_mfma_f32_16x16x32_bf16 v[16:19], v[188:191], v[202:205], v[16:19]
	ds_read_b64_tr_b16 v[188:189], v149 offset:52288
	ds_read_b64_tr_b16 v[190:191], v149 offset:54464
	s_waitcnt lgkmcnt(2)
	v_mfma_f32_16x16x32_bf16 v[52:55], v[206:209], v[184:187], v[52:55]
	v_mfma_f32_16x16x32_bf16 v[160:163], v[206:209], v[192:195], v[160:163]
	v_mfma_f32_16x16x32_bf16 v[164:167], v[206:209], v[196:199], v[164:167]
	v_mfma_f32_16x16x32_bf16 v[48:51], v[206:209], v[202:205], v[48:51]
	ds_read_b64_tr_b16 v[208:209], v149 offset:54496
	ds_read_b64_tr_b16 v[206:207], v149 offset:52320
	s_waitcnt lgkmcnt(2)
	v_mfma_f32_16x16x32_bf16 v[172:175], v[188:191], v[184:187], v[172:175]
	v_mfma_f32_16x16x32_bf16 v[176:179], v[188:191], v[192:195], v[176:179]
	v_mfma_f32_16x16x32_bf16 v[180:183], v[188:191], v[196:199], v[180:183]
	v_mfma_f32_16x16x32_bf16 v[168:171], v[188:191], v[202:205], v[168:171]
	s_waitcnt lgkmcnt(0)
	v_mfma_f32_16x16x32_bf16 v[20:23], v[206:209], v[184:187], v[20:23]
	ds_read_b64_tr_b16 v[186:187], v150 offset:36992
	ds_read_b64_tr_b16 v[184:185], v150 offset:34816
	ds_read_b128 v[188:191], v158 offset:128
	v_mfma_f32_16x16x32_bf16 v[28:31], v[206:209], v[192:195], v[28:31]
	ds_read_b128 v[192:195], v158 offset:4480
	v_mfma_f32_16x16x32_bf16 v[36:39], v[206:209], v[196:199], v[36:39]
	ds_read_b128 v[196:199], v158 offset:8832
	v_mfma_f32_16x16x32_bf16 v[44:47], v[206:209], v[202:205], v[44:47]
	ds_read_b128 v[202:205], v158 offset:13184
	ds_read_b64_tr_b16 v[206:207], v150 offset:34848
	ds_read_b64_tr_b16 v[208:209], v150 offset:37024
	s_waitcnt lgkmcnt(5)
	v_mfma_f32_16x16x32_bf16 v[24:27], v[184:187], v[188:191], v[24:27]
	s_waitcnt lgkmcnt(4)
	v_mfma_f32_16x16x32_bf16 v[32:35], v[184:187], v[192:195], v[32:35]
	s_waitcnt lgkmcnt(3)
	v_mfma_f32_16x16x32_bf16 v[40:43], v[184:187], v[196:199], v[40:43]
	s_waitcnt lgkmcnt(2)
	v_mfma_f32_16x16x32_bf16 v[16:19], v[184:187], v[202:205], v[16:19]
	ds_read_b64_tr_b16 v[184:185], v150 offset:34880
	ds_read_b64_tr_b16 v[186:187], v150 offset:37056
	s_waitcnt lgkmcnt(2)
	v_mfma_f32_16x16x32_bf16 v[52:55], v[206:209], v[188:191], v[52:55]
	v_mfma_f32_16x16x32_bf16 v[160:163], v[206:209], v[192:195], v[160:163]
	v_mfma_f32_16x16x32_bf16 v[164:167], v[206:209], v[196:199], v[164:167]
	v_mfma_f32_16x16x32_bf16 v[206:209], v[206:209], v[202:205], v[48:51]
	s_nop 2
	ds_read_b64_tr_b16 v[50:51], v150 offset:37088
	ds_read_b64_tr_b16 v[48:49], v150 offset:34912
	s_waitcnt lgkmcnt(2)
	v_mfma_f32_16x16x32_bf16 v[172:175], v[184:187], v[188:191], v[172:175]
	v_mfma_f32_16x16x32_bf16 v[176:179], v[184:187], v[192:195], v[176:179]
	v_mfma_f32_16x16x32_bf16 v[180:183], v[184:187], v[196:199], v[180:183]
	v_mfma_f32_16x16x32_bf16 v[168:171], v[184:187], v[202:205], v[168:171]
	s_waitcnt lgkmcnt(0)
	v_mfma_f32_16x16x32_bf16 v[20:23], v[48:51], v[188:191], v[20:23]
	v_mfma_f32_16x16x32_bf16 v[184:187], v[48:51], v[192:195], v[28:31]
	s_nop 2
	ds_read_b64_tr_b16 v[28:29], v150 offset:52224
	ds_read_b64_tr_b16 v[30:31], v150 offset:54400
	ds_read_b128 v[210:213], v158 offset:4544
	ds_read_b128 v[214:217], v158 offset:8896
	v_mfma_f32_16x16x32_bf16 v[188:191], v[48:51], v[196:199], v[36:39]
	ds_read_b128 v[196:199], v158 offset:192
	v_mfma_f32_16x16x32_bf16 v[192:195], v[48:51], v[202:205], v[44:47]
	s_waitcnt lgkmcnt(0)
; __device__ __forceinline__ unsigned pk2(float lo, float hi) { return f2bf(lo) | (f2bf(hi) << 16); }
; __device__ __forceinline__ float bflo(unsigned w) { return __uint_as_float(w << 16); }
; __device__ __forceinline__ float bfhi(unsigned w) { return __uint_as_float(w & 0xffff0000u); }
; __device__ __forceinline__ void spatial_phase(LAS unsigned char* lds, const bf16* Z, bf16* GT, const float* vstat, const float* lng, const float* lnb, const float* wsp, const float* bsp) {
;     ...
;                 for (int tt = 0; tt < 4; ++tt) acc[ct][tt] = __builtin_amdgcn_mfma_f32_16x16x32_bf16(vf[ct], wf[tt], acc[ct][tt], 0, 0, 0);
;         }
; #pragma unroll
;         for (int tt = 0; tt < 4; ++tt) { const int t = th * 64 + tt * 16 + fr; const float bv_ = bsv[tt];
; #pragma unroll
;             for (int ct = 0; ct < 4; ++ct) { const u32x2 w = uw[tt][ct]; bf16* up = GT + zpan + (size_t)g * 65536 + (size_t)(zrow + t) * 256 + cq * 64 + ct * 16 + 4 * fq;
;                 u32x2 o; o.x = pk2(bflo(w.x) * (acc[ct][tt][0] + bv_), bfhi(w.x) * (acc[ct][tt][1] + bv_)); o.y = pk2(bflo(w.y) * (acc[ct][tt][2] + bv_), bfhi(w.y) * (acc[ct][tt][3] + bv_)); *(u32x2*)up = o; } }
	v_mfma_f32_16x16x32_bf16 v[202:205], v[28:31], v[196:199], v[24:27]
	ds_read_b128 v[218:221], v158 offset:13248
	s_nop 1
	ds_read_b64_tr_b16 v[24:25], v150 offset:52256
	ds_read_b64_tr_b16 v[26:27], v150 offset:54432
	v_mfma_f32_16x16x32_bf16 v[48:51], v[28:31], v[210:213], v[32:35]
	v_mfma_f32_16x16x32_bf16 v[36:39], v[28:31], v[214:217], v[40:43]
	s_waitcnt lgkmcnt(2)
	v_mfma_f32_16x16x32_bf16 v[28:31], v[28:31], v[218:221], v[16:19]
	s_nop 2
	ds_read_b64_tr_b16 v[18:19], v150 offset:54464
	ds_read_b64_tr_b16 v[16:17], v150 offset:52288
	s_waitcnt lgkmcnt(2)
	v_mfma_f32_16x16x32_bf16 v[44:47], v[24:27], v[214:217], v[164:167]
	s_waitcnt lgkmcnt(0)
	v_mfma_f32_16x16x32_bf16 v[164:167], v[16:19], v[196:199], v[172:175]
	s_nop 2
	ds_read_b64_tr_b16 v[172:173], v150 offset:52320
	ds_read_b64_tr_b16 v[174:175], v150 offset:54496
	v_mfma_f32_16x16x32_bf16 v[222:225], v[24:27], v[196:199], v[52:55]
	v_mfma_f32_16x16x32_bf16 v[52:55], v[16:19], v[210:213], v[176:179]
	v_mfma_f32_16x16x32_bf16 v[32:35], v[16:19], v[214:217], v[180:183]
	v_mfma_f32_16x16x32_bf16 v[16:19], v[16:19], v[218:221], v[168:171]
	s_waitcnt lgkmcnt(0)
	v_mfma_f32_16x16x32_bf16 v[168:171], v[172:175], v[196:199], v[20:23]
	v_mfma_f32_16x16x32_bf16 v[176:179], v[172:175], v[210:213], v[184:187]
	v_mfma_f32_16x16x32_bf16 v[40:43], v[172:175], v[214:217], v[188:191]
	v_mfma_f32_16x16x32_bf16 v[20:23], v[172:175], v[218:221], v[192:195]
	v_mov_b32_e32 v174, v202
	v_mov_b32_e32 v175, v204
	s_waitcnt vmcnt(15)
	v_lshlrev_b32_e32 v173, 16, v131
	v_lshlrev_b32_e32 v172, 16, v130
	v_pk_add_f32 v[174:175], v[84:85], v[174:175] op_sel_hi:[0,1]
	v_mov_b32_e32 v204, v203
	v_pk_mul_f32 v[172:173], v[174:175], v[172:173]
	v_and_b32_e32 v131, 0xffff0000, v131
	v_and_b32_e32 v130, 0xffff0000, v130
	v_pk_add_f32 v[174:175], v[84:85], v[204:205] op_sel_hi:[0,1]
	v_pk_mul_f32 v[130:131], v[174:175], v[130:131]
	v_cvt_pk_bf16_f32 v131, v173, v131
	v_cvt_pk_bf16_f32 v130, v172, v130
	v_mov_b32_e32 v172, v222
	v_mov_b32_e32 v173, v224
	global_store_dwordx2 v[122:123], v[130:131], off
	s_waitcnt vmcnt(15)
	v_lshlrev_b32_e32 v131, 16, v129
	v_lshlrev_b32_e32 v130, 16, v128
	v_pk_add_f32 v[172:173], v[84:85], v[172:173] op_sel_hi:[0,1]
	v_mov_b32_e32 v224, v223
	v_pk_mul_f32 v[130:131], v[172:173], v[130:131]
	v_and_b32_e32 v129, 0xffff0000, v129
	v_and_b32_e32 v128, 0xffff0000, v128
	v_pk_add_f32 v[172:173], v[84:85], v[224:225] op_sel_hi:[0,1]
	v_pk_mul_f32 v[128:129], v[172:173], v[128:129]
	v_cvt_pk_bf16_f32 v129, v131, v129
	v_cvt_pk_bf16_f32 v128, v130, v128
	v_mov_b32_e32 v130, v164
	v_mov_b32_e32 v131, v166
	global_store_dwordx2 v[122:123], v[128:129], off offset:32
	s_waitcnt vmcnt(15)
	v_lshlrev_b32_e32 v129, 16, v127
	v_lshlrev_b32_e32 v128, 16, v126
	v_pk_add_f32 v[130:131], v[84:85], v[130:131] op_sel_hi:[0,1]
	v_mov_b32_e32 v166, v165
	v_pk_mul_f32 v[128:129], v[130:131], v[128:129]
	v_and_b32_e32 v127, 0xffff0000, v127
	v_and_b32_e32 v126, 0xffff0000, v126
	v_pk_add_f32 v[130:131], v[84:85], v[166:167] op_sel_hi:[0,1]
	v_pk_mul_f32 v[126:127], v[130:131], v[126:127]
	v_cvt_pk_bf16_f32 v127, v129, v127
	v_cvt_pk_bf16_f32 v126, v128, v126
	v_mov_b32_e32 v128, v168
	v_mov_b32_e32 v129, v170
	global_store_dwordx2 v[122:123], v[126:127], off offset:64
	s_waitcnt vmcnt(15)
	v_lshlrev_b32_e32 v127, 16, v125
	v_lshlrev_b32_e32 v126, 16, v124
	v_pk_add_f32 v[128:129], v[84:85], v[128:129] op_sel_hi:[0,1]
	v_mov_b32_e32 v170, v169
	v_pk_mul_f32 v[126:127], v[128:129], v[126:127]
	v_and_b32_e32 v125, 0xffff0000, v125
	v_and_b32_e32 v124, 0xffff0000, v124
	v_pk_add_f32 v[128:129], v[84:85], v[170:171] op_sel_hi:[0,1]
	v_pk_mul_f32 v[124:125], v[128:129], v[124:125]
	v_cvt_pk_bf16_f32 v125, v127, v125
	v_cvt_pk_bf16_f32 v124, v126, v124
	global_store_dwordx2 v[122:123], v[124:125], off offset:96
	v_mov_b32_e32 v125, v50
	v_mov_b32_e32 v50, v49
	s_waitcnt vmcnt(15)
	v_lshlrev_b32_e32 v123, 16, v121
	v_lshlrev_b32_e32 v122, 16, v120
	v_mov_b32_e32 v124, v48
	v_and_b32_e32 v121, 0xffff0000, v121
	v_and_b32_e32 v120, 0xffff0000, v120
	v_pk_add_f32 v[48:49], v[86:87], v[50:51] op_sel_hi:[0,1]
	v_mfma_f32_16x16x32_bf16 v[160:163], v[24:27], v[210:213], v[160:163]
	v_add_f32_e64 v124, v86, v124
	v_add_f32_e64 v125, v86, v125
	v_pk_mul_f32 v[48:49], v[48:49], v[120:121]
	v_pk_mul_f32 v[122:123], v[124:125], v[122:123]
	v_cvt_pk_bf16_f32 v49, v123, v49
	v_cvt_pk_bf16_f32 v48, v122, v48
	s_nop 1
	v_mov_b32_e32 v50, v160
	s_nop 0
	v_mov_b32_e32 v51, v162
	global_store_dwordx2 v[110:111], v[48:49], off
	s_waitcnt vmcnt(15)
	v_lshlrev_b32_e32 v49, 16, v119
	v_lshlrev_b32_e32 v48, 16, v118
	v_pk_add_f32 v[50:51], v[86:87], v[50:51] op_sel_hi:[0,1]
	v_mov_b32_e32 v162, v161
	v_pk_mul_f32 v[48:49], v[50:51], v[48:49]
	v_and_b32_e32 v51, 0xffff0000, v119
	v_and_b32_e32 v50, 0xffff0000, v118
	v_pk_add_f32 v[118:119], v[86:87], v[162:163] op_sel_hi:[0,1]
	v_pk_mul_f32 v[50:51], v[118:119], v[50:51]
	v_cvt_pk_bf16_f32 v49, v49, v51
	v_cvt_pk_bf16_f32 v48, v48, v50
	v_mov_b32_e32 v50, v52
	v_mov_b32_e32 v51, v54
	global_store_dwordx2 v[110:111], v[48:49], off offset:32
	s_waitcnt vmcnt(15)
	v_lshlrev_b32_e32 v49, 16, v117
	v_lshlrev_b32_e32 v48, 16, v116
	v_pk_add_f32 v[50:51], v[86:87], v[50:51] op_sel_hi:[0,1]
	v_mov_b32_e32 v54, v53
	v_pk_mul_f32 v[48:49], v[50:51], v[48:49]
	v_and_b32_e32 v51, 0xffff0000, v117
	v_and_b32_e32 v50, 0xffff0000, v116
	v_pk_add_f32 v[52:53], v[86:87], v[54:55] op_sel_hi:[0,1]
	v_pk_mul_f32 v[50:51], v[52:53], v[50:51]
	v_cvt_pk_bf16_f32 v49, v49, v51
	v_cvt_pk_bf16_f32 v48, v48, v50
	v_mov_b32_e32 v50, v176
	v_mov_b32_e32 v51, v178
	global_store_dwordx2 v[110:111], v[48:49], off offset:64
	s_waitcnt vmcnt(15)
; __device__ __forceinline__ unsigned pk2(float lo, float hi) { return f2bf(lo) | (f2bf(hi) << 16); }
; __device__ __forceinline__ float bflo(unsigned w) { return __uint_as_float(w << 16); }
; __device__ __forceinline__ float bfhi(unsigned w) { return __uint_as_float(w & 0xffff0000u); }
; __device__ __forceinline__ void spatial_phase(LAS unsigned char* lds, const bf16* Z, bf16* GT, const float* vstat, const float* lng, const float* lnb, const float* wsp, const float* bsp) {
;     ...
;         for (int tt = 0; tt < 4; ++tt) { const int t = th * 64 + tt * 16 + fr; const float bv_ = bsv[tt];
; #pragma unroll
;             for (int ct = 0; ct < 4; ++ct) { const u32x2 w = uw[tt][ct]; bf16* up = GT + zpan + (size_t)g * 65536 + (size_t)(zrow + t) * 256 + cq * 64 + ct * 16 + 4 * fq;
;                 u32x2 o; o.x = pk2(bflo(w.x) * (acc[ct][tt][0] + bv_), bfhi(w.x) * (acc[ct][tt][1] + bv_)); o.y = pk2(bflo(w.y) * (acc[ct][tt][2] + bv_), bfhi(w.y) * (acc[ct][tt][3] + bv_)); *(u32x2*)up = o; } }
	v_lshlrev_b32_e32 v49, 16, v115
	v_lshlrev_b32_e32 v48, 16, v114
	v_pk_add_f32 v[50:51], v[86:87], v[50:51] op_sel_hi:[0,1]
	v_mov_b32_e32 v178, v177
	v_pk_mul_f32 v[48:49], v[50:51], v[48:49]
	v_and_b32_e32 v51, 0xffff0000, v115
	v_and_b32_e32 v50, 0xffff0000, v114
	v_pk_add_f32 v[52:53], v[86:87], v[178:179] op_sel_hi:[0,1]
	v_pk_mul_f32 v[50:51], v[52:53], v[50:51]
	v_cvt_pk_bf16_f32 v49, v49, v51
	v_cvt_pk_bf16_f32 v48, v48, v50
	v_mov_b32_e32 v50, v36
	v_mov_b32_e32 v51, v38
	global_store_dwordx2 v[110:111], v[48:49], off offset:96
	s_waitcnt vmcnt(15)
	v_lshlrev_b32_e32 v49, 16, v113
	v_lshlrev_b32_e32 v48, 16, v112
	v_pk_add_f32 v[50:51], v[88:89], v[50:51] op_sel_hi:[0,1]
	v_mov_b32_e32 v38, v37
	v_pk_mul_f32 v[48:49], v[50:51], v[48:49]
	v_and_b32_e32 v51, 0xffff0000, v113
	v_and_b32_e32 v50, 0xffff0000, v112
	v_pk_add_f32 v[36:37], v[88:89], v[38:39] op_sel_hi:[0,1]
	v_pk_mul_f32 v[36:37], v[36:37], v[50:51]
	v_and_b32_sdwa v38, v49, v159 dst_sel:DWORD dst_unused:UNUSED_PAD src0_sel:WORD_1 src1_sel:DWORD
	v_and_b32_sdwa v39, v48, v159 dst_sel:DWORD dst_unused:UNUSED_PAD src0_sel:WORD_1 src1_sel:DWORD
	v_add3_u32 v39, v48, v39, s90
	v_add3_u32 v38, v49, v38, s90
	v_and_b32_sdwa v48, v37, v159 dst_sel:DWORD dst_unused:UNUSED_PAD src0_sel:WORD_1 src1_sel:DWORD
	v_and_b32_sdwa v49, v36, v159 dst_sel:DWORD dst_unused:UNUSED_PAD src0_sel:WORD_1 src1_sel:DWORD
	v_add3_u32 v37, v37, v48, s90
	v_add3_u32 v36, v36, v49, s90
	v_and_b32_e32 v37, 0xffff0000, v37
	v_and_b32_e32 v36, 0xffff0000, v36
	v_or_b32_sdwa v37, v37, v38 dst_sel:DWORD dst_unused:UNUSED_PAD src0_sel:DWORD src1_sel:WORD_1
	v_or_b32_sdwa v36, v36, v39 dst_sel:DWORD dst_unused:UNUSED_PAD src0_sel:DWORD src1_sel:WORD_1
	v_mov_b32_e32 v38, v44
	v_mov_b32_e32 v39, v46
	global_store_dwordx2 v[100:101], v[36:37], off
	s_waitcnt vmcnt(15)
	v_lshlrev_b32_e32 v37, 16, v109
	v_lshlrev_b32_e32 v36, 16, v108
	v_pk_add_f32 v[38:39], v[88:89], v[38:39] op_sel_hi:[0,1]
	v_mov_b32_e32 v46, v45
	v_pk_mul_f32 v[36:37], v[38:39], v[36:37]
	v_and_b32_e32 v39, 0xffff0000, v109
	v_and_b32_e32 v38, 0xffff0000, v108
	v_pk_add_f32 v[44:45], v[88:89], v[46:47] op_sel_hi:[0,1]
	v_pk_mul_f32 v[38:39], v[44:45], v[38:39]
	v_cvt_pk_bf16_f32 v37, v37, v39
	v_cvt_pk_bf16_f32 v36, v36, v38
	v_mov_b32_e32 v38, v32
	v_mov_b32_e32 v39, v34
	global_store_dwordx2 v[100:101], v[36:37], off offset:32
	s_waitcnt vmcnt(15)
	v_lshlrev_b32_e32 v37, 16, v107
	v_lshlrev_b32_e32 v36, 16, v106
	v_pk_add_f32 v[38:39], v[88:89], v[38:39] op_sel_hi:[0,1]
	v_mov_b32_e32 v34, v33
	v_pk_mul_f32 v[36:37], v[38:39], v[36:37]
	v_and_b32_e32 v39, 0xffff0000, v107
	v_and_b32_e32 v38, 0xffff0000, v106
	v_pk_add_f32 v[32:33], v[88:89], v[34:35] op_sel_hi:[0,1]
	v_pk_mul_f32 v[32:33], v[32:33], v[38:39]
	v_and_b32_sdwa v34, v37, v159 dst_sel:DWORD dst_unused:UNUSED_PAD src0_sel:WORD_1 src1_sel:DWORD
	v_and_b32_sdwa v35, v36, v159 dst_sel:DWORD dst_unused:UNUSED_PAD src0_sel:WORD_1 src1_sel:DWORD
	v_add3_u32 v35, v36, v35, s90
	v_add3_u32 v34, v37, v34, s90
	v_and_b32_sdwa v36, v33, v159 dst_sel:DWORD dst_unused:UNUSED_PAD src0_sel:WORD_1 src1_sel:DWORD
	v_and_b32_sdwa v37, v32, v159 dst_sel:DWORD dst_unused:UNUSED_PAD src0_sel:WORD_1 src1_sel:DWORD
	v_add3_u32 v33, v33, v36, s90
	v_add3_u32 v32, v32, v37, s90
	v_and_b32_e32 v33, 0xffff0000, v33
	v_and_b32_e32 v32, 0xffff0000, v32
	v_or_b32_sdwa v33, v33, v34 dst_sel:DWORD dst_unused:UNUSED_PAD src0_sel:DWORD src1_sel:WORD_1
	v_or_b32_sdwa v32, v32, v35 dst_sel:DWORD dst_unused:UNUSED_PAD src0_sel:DWORD src1_sel:WORD_1
	v_mov_b32_e32 v34, v40
	v_mov_b32_e32 v35, v42
	global_store_dwordx2 v[100:101], v[32:33], off offset:64
	s_waitcnt vmcnt(15)
	v_lshlrev_b32_e32 v33, 16, v105
	v_lshlrev_b32_e32 v32, 16, v104
	v_pk_add_f32 v[34:35], v[88:89], v[34:35] op_sel_hi:[0,1]
	v_mov_b32_e32 v42, v41
	v_pk_mul_f32 v[32:33], v[34:35], v[32:33]
	v_and_b32_e32 v35, 0xffff0000, v105
	v_and_b32_e32 v34, 0xffff0000, v104
	v_pk_add_f32 v[36:37], v[88:89], v[42:43] op_sel_hi:[0,1]
	v_pk_mul_f32 v[34:35], v[36:37], v[34:35]
	v_cvt_pk_bf16_f32 v33, v33, v35
	v_cvt_pk_bf16_f32 v32, v32, v34
	v_mov_b32_e32 v34, v28
	v_mov_b32_e32 v35, v30
	global_store_dwordx2 v[100:101], v[32:33], off offset:96
	s_waitcnt vmcnt(15)
	v_lshlrev_b32_e32 v33, 16, v103
	v_lshlrev_b32_e32 v32, 16, v102
	v_pk_add_f32 v[34:35], v[90:91], v[34:35] op_sel_hi:[0,1]
	v_mov_b32_e32 v30, v29
	v_pk_mul_f32 v[32:33], v[34:35], v[32:33]
	v_and_b32_e32 v35, 0xffff0000, v103
	v_and_b32_e32 v34, 0xffff0000, v102
	v_pk_add_f32 v[28:29], v[90:91], v[30:31] op_sel_hi:[0,1]
	v_mfma_f32_16x16x32_bf16 v[24:27], v[24:27], v[218:221], v[206:209]
	v_mul_f32_e64 v28, v28, v34
	v_mul_f32_e64 v29, v29, v35
	v_and_b32_sdwa v30, v33, v159 dst_sel:DWORD dst_unused:UNUSED_PAD src0_sel:WORD_1 src1_sel:DWORD
	v_and_b32_sdwa v31, v32, v159 dst_sel:DWORD dst_unused:UNUSED_PAD src0_sel:WORD_1 src1_sel:DWORD
	v_add3_u32 v31, v32, v31, s90
	v_add3_u32 v30, v33, v30, s90
	v_and_b32_sdwa v32, v29, v159 dst_sel:DWORD dst_unused:UNUSED_PAD src0_sel:WORD_1 src1_sel:DWORD
	v_and_b32_sdwa v33, v28, v159 dst_sel:DWORD dst_unused:UNUSED_PAD src0_sel:WORD_1 src1_sel:DWORD
	v_add3_u32 v29, v29, v32, s90
	v_add3_u32 v28, v28, v33, s90
	v_and_b32_e32 v29, 0xffff0000, v29
	v_and_b32_e32 v28, 0xffff0000, v28
	v_or_b32_sdwa v29, v29, v30 dst_sel:DWORD dst_unused:UNUSED_PAD src0_sel:DWORD src1_sel:WORD_1
	v_or_b32_sdwa v28, v28, v31 dst_sel:DWORD dst_unused:UNUSED_PAD src0_sel:DWORD src1_sel:WORD_1
	v_mov_b32_e32 v30, v24
	v_mov_b32_e32 v31, v26
	global_store_dwordx2 v[92:93], v[28:29], off
	s_waitcnt vmcnt(15)
; __device__ __forceinline__ unsigned pk2(float lo, float hi) { return f2bf(lo) | (f2bf(hi) << 16); }
; __device__ __forceinline__ float bflo(unsigned w) { return __uint_as_float(w << 16); }
; __device__ __forceinline__ float bfhi(unsigned w) { return __uint_as_float(w & 0xffff0000u); }
; __device__ __forceinline__ void spatial_phase(LAS unsigned char* lds, const bf16* Z, bf16* GT, const float* vstat, const float* lng, const float* lnb, const float* wsp, const float* bsp) {
;     ...
;         for (int tt = 0; tt < 4; ++tt) { const int t = th * 64 + tt * 16 + fr; const float bv_ = bsv[tt];
; #pragma unroll
;             for (int ct = 0; ct < 4; ++ct) { const u32x2 w = uw[tt][ct]; bf16* up = GT + zpan + (size_t)g * 65536 + (size_t)(zrow + t) * 256 + cq * 64 + ct * 16 + 4 * fq;
;                 u32x2 o; o.x = pk2(bflo(w.x) * (acc[ct][tt][0] + bv_), bfhi(w.x) * (acc[ct][tt][1] + bv_)); o.y = pk2(bflo(w.y) * (acc[ct][tt][2] + bv_), bfhi(w.y) * (acc[ct][tt][3] + bv_)); *(u32x2*)up = o; } }
;         __syncthreads();
	v_lshlrev_b32_e32 v29, 16, v99
	v_lshlrev_b32_e32 v28, 16, v98
	v_pk_add_f32 v[30:31], v[90:91], v[30:31] op_sel_hi:[0,1]
	v_mov_b32_e32 v26, v25
	v_pk_mul_f32 v[28:29], v[30:31], v[28:29]
	v_and_b32_e32 v31, 0xffff0000, v99
	v_and_b32_e32 v30, 0xffff0000, v98
	v_pk_add_f32 v[24:25], v[90:91], v[26:27] op_sel_hi:[0,1]
	v_pk_mul_f32 v[24:25], v[24:25], v[30:31]
	v_and_b32_sdwa v26, v29, v159 dst_sel:DWORD dst_unused:UNUSED_PAD src0_sel:WORD_1 src1_sel:DWORD
	v_and_b32_sdwa v27, v28, v159 dst_sel:DWORD dst_unused:UNUSED_PAD src0_sel:WORD_1 src1_sel:DWORD
	v_add3_u32 v27, v28, v27, s90
	v_add3_u32 v26, v29, v26, s90
	v_and_b32_sdwa v28, v25, v159 dst_sel:DWORD dst_unused:UNUSED_PAD src0_sel:WORD_1 src1_sel:DWORD
	v_and_b32_sdwa v29, v24, v159 dst_sel:DWORD dst_unused:UNUSED_PAD src0_sel:WORD_1 src1_sel:DWORD
	v_add3_u32 v25, v25, v28, s90
	v_add3_u32 v24, v24, v29, s90
	v_and_b32_e32 v25, 0xffff0000, v25
	v_and_b32_e32 v24, 0xffff0000, v24
	v_or_b32_sdwa v25, v25, v26 dst_sel:DWORD dst_unused:UNUSED_PAD src0_sel:DWORD src1_sel:WORD_1
	v_or_b32_sdwa v24, v24, v27 dst_sel:DWORD dst_unused:UNUSED_PAD src0_sel:DWORD src1_sel:WORD_1
	v_mov_b32_e32 v26, v16
	v_mov_b32_e32 v27, v18
	global_store_dwordx2 v[92:93], v[24:25], off offset:32
	s_waitcnt vmcnt(15)
	v_lshlrev_b32_e32 v25, 16, v97
	v_lshlrev_b32_e32 v24, 16, v96
	v_pk_add_f32 v[26:27], v[90:91], v[26:27] op_sel_hi:[0,1]
	v_mov_b32_e32 v18, v17
	v_pk_mul_f32 v[24:25], v[26:27], v[24:25]
	v_and_b32_e32 v27, 0xffff0000, v97
	v_and_b32_e32 v26, 0xffff0000, v96
	v_pk_add_f32 v[16:17], v[90:91], v[18:19] op_sel_hi:[0,1]
	v_pk_mul_f32 v[16:17], v[16:17], v[26:27]
	v_and_b32_sdwa v18, v25, v159 dst_sel:DWORD dst_unused:UNUSED_PAD src0_sel:WORD_1 src1_sel:DWORD
	v_and_b32_sdwa v19, v24, v159 dst_sel:DWORD dst_unused:UNUSED_PAD src0_sel:WORD_1 src1_sel:DWORD
	v_add3_u32 v19, v24, v19, s90
	v_add3_u32 v18, v25, v18, s90
	v_and_b32_sdwa v24, v17, v159 dst_sel:DWORD dst_unused:UNUSED_PAD src0_sel:WORD_1 src1_sel:DWORD
	v_and_b32_sdwa v25, v16, v159 dst_sel:DWORD dst_unused:UNUSED_PAD src0_sel:WORD_1 src1_sel:DWORD
	v_add3_u32 v17, v17, v24, s90
	v_add3_u32 v16, v16, v25, s90
	v_and_b32_e32 v17, 0xffff0000, v17
	v_and_b32_e32 v16, 0xffff0000, v16
	v_or_b32_sdwa v17, v17, v18 dst_sel:DWORD dst_unused:UNUSED_PAD src0_sel:DWORD src1_sel:WORD_1
	v_or_b32_sdwa v16, v16, v19 dst_sel:DWORD dst_unused:UNUSED_PAD src0_sel:DWORD src1_sel:WORD_1
	v_mov_b32_e32 v18, v20
	v_mov_b32_e32 v19, v22
	global_store_dwordx2 v[92:93], v[16:17], off offset:64
	s_waitcnt vmcnt(15)
	v_lshlrev_b32_e32 v17, 16, v95
	v_lshlrev_b32_e32 v16, 16, v94
	v_pk_add_f32 v[18:19], v[90:91], v[18:19] op_sel_hi:[0,1]
	v_mov_b32_e32 v22, v21
	v_pk_mul_f32 v[16:17], v[18:19], v[16:17]
	v_and_b32_e32 v19, 0xffff0000, v95
	v_and_b32_e32 v18, 0xffff0000, v94
	v_pk_add_f32 v[20:21], v[90:91], v[22:23] op_sel_hi:[0,1]
	v_pk_mul_f32 v[18:19], v[20:21], v[18:19]
	v_cvt_pk_bf16_f32 v17, v17, v19
	v_cvt_pk_bf16_f32 v16, v16, v18
	global_store_dwordx2 v[92:93], v[16:17], off offset:96
	s_barrier
	s_load_dword s0, s[88:89], 0x128
	s_waitcnt lgkmcnt(0)
	s_add_i32 s96, s96, s0
	s_cmpk_lt_i32 s96, 0x800
	s_cbranch_scc0 .LBB0_765
.LBB0_761:
	s_and_b32 s0, s96, 15
	s_cmp_eq_u32 s0, s92
	s_cbranch_scc1 .LBB0_763
	s_lshl_b32 s80, s0, 16
	v_lshl_add_u64 v[0:1], v[60:61], 0, s[80:81]
	v_mov_b32_e32 v65, v59
	v_lshl_add_u64 v[2:3], v[0:1], 0, v[64:65]
	global_load_dwordx4 v[2:5], v[2:3], off
	v_mov_b32_e32 v6, s81
	v_mov_b32_e32 v67, v59
	v_mov_b32_e32 v69, v59
	v_mov_b32_e32 v71, v59
	v_mov_b32_e32 v73, v59
	v_mov_b32_e32 v75, v59
	v_mov_b32_e32 v77, v59
	v_mov_b32_e32 v79, v59
	s_lshl_b32 s1, s0, 7
	v_add_lshl_u32 v16, s1, v57, 2
	s_mov_b32 s92, s0
	s_waitcnt vmcnt(0)
	v_cndmask_b32_e64 v6, v2, v6, s[6:7]
	v_cndmask_b32_e64 v2, v6, v2, s[8:9]
	v_cndmask_b32_e64 v3, 0, v3, s[8:9]
	v_cndmask_b32_e64 v4, v4, 0, s[10:11]
	v_cndmask_b32_e64 v5, v5, 0, s[12:13]
	v_cvt_pk_bf16_f32 v2, v2, v3
	v_cvt_pk_bf16_f32 v3, v4, v5
	ds_write_b64 v151, v[2:3]
	v_lshl_add_u64 v[2:3], v[0:1], 0, v[66:67]
	global_load_dwordx4 v[2:5], v[2:3], off
	v_mov_b32_e32 v6, s81
	s_waitcnt vmcnt(0)
	v_cndmask_b32_e64 v6, v2, v6, s[14:15]
	v_cndmask_b32_e64 v2, v6, v2, s[16:17]
	v_cndmask_b32_e64 v3, 0, v3, s[16:17]
	v_cndmask_b32_e64 v4, v4, 0, s[18:19]
	v_cndmask_b32_e64 v5, v5, 0, s[20:21]
	v_cvt_pk_bf16_f32 v2, v2, v3
	v_cvt_pk_bf16_f32 v3, v4, v5
	ds_write_b64 v152, v[2:3]
	v_lshl_add_u64 v[2:3], v[0:1], 0, v[68:69]
	global_load_dwordx4 v[2:5], v[2:3], off
	v_mov_b32_e32 v6, s81
	s_waitcnt vmcnt(0)
	v_cndmask_b32_e64 v6, v2, v6, s[22:23]
	v_cndmask_b32_e64 v2, v6, v2, s[24:25]
	v_cndmask_b32_e64 v3, 0, v3, s[24:25]
	v_cndmask_b32_e64 v4, v4, 0, s[26:27]
	v_cndmask_b32_e64 v5, v5, 0, s[28:29]
	v_cvt_pk_bf16_f32 v2, v2, v3
	v_cvt_pk_bf16_f32 v3, v4, v5
	ds_write_b64 v151, v[2:3] offset:8704
	v_lshl_add_u64 v[2:3], v[0:1], 0, v[70:71]
	global_load_dwordx4 v[2:5], v[2:3], off
	v_mov_b32_e32 v6, s81
	s_waitcnt vmcnt(0)
	v_cndmask_b32_e64 v6, v2, v6, s[30:31]
	v_cndmask_b32_e64 v2, v6, v2, s[34:35]
	v_cndmask_b32_e64 v3, 0, v3, s[34:35]
	v_cndmask_b32_e64 v4, v4, 0, s[36:37]
	v_cndmask_b32_e64 v5, v5, 0, s[38:39]
	v_cvt_pk_bf16_f32 v2, v2, v3
	v_cvt_pk_bf16_f32 v3, v4, v5
	ds_write_b64 v153, v[2:3]
	v_lshl_add_u64 v[2:3], v[0:1], 0, v[72:73]
	global_load_dwordx4 v[2:5], v[2:3], off
	v_mov_b32_e32 v6, s81
	s_waitcnt vmcnt(0)
	v_cndmask_b32_e64 v6, v2, v6, s[40:41]
	v_cndmask_b32_e64 v2, v6, v2, s[42:43]
	v_cndmask_b32_e64 v3, 0, v3, s[42:43]
	v_cndmask_b32_e64 v4, v4, 0, s[44:45]
	v_cndmask_b32_e64 v5, v5, 0, s[46:47]
	v_cvt_pk_bf16_f32 v2, v2, v3
	v_cvt_pk_bf16_f32 v3, v4, v5
	ds_write_b64 v151, v[2:3] offset:17408
	v_lshl_add_u64 v[2:3], v[0:1], 0, v[74:75]
	global_load_dwordx4 v[2:5], v[2:3], off
	v_mov_b32_e32 v6, s81
	s_waitcnt vmcnt(0)
	v_cndmask_b32_e64 v6, v2, v6, s[48:49]
	v_cndmask_b32_e64 v2, v6, v2, s[50:51]
	v_cndmask_b32_e64 v3, 0, v3, s[50:51]
	v_cndmask_b32_e64 v4, v4, 0, s[52:53]
	v_cndmask_b32_e64 v5, v5, 0, s[54:55]
	v_cvt_pk_bf16_f32 v2, v2, v3
	v_cvt_pk_bf16_f32 v3, v4, v5
	ds_write_b64 v154, v[2:3]
	v_lshl_add_u64 v[2:3], v[0:1], 0, v[76:77]
	global_load_dwordx4 v[2:5], v[2:3], off
	v_mov_b32_e32 v6, s81
	v_lshl_add_u64 v[0:1], v[0:1], 0, v[78:79]
	s_waitcnt vmcnt(0)
	v_cndmask_b32_e64 v6, v2, v6, s[56:57]
	v_cndmask_b32_e64 v2, v6, v2, s[58:59]
	v_cndmask_b32_e64 v3, 0, v3, s[58:59]
	v_cndmask_b32_e64 v4, v4, 0, s[60:61]
	v_cndmask_b32_e64 v5, v5, 0, s[62:63]
	v_cvt_pk_bf16_f32 v2, v2, v3
	v_cvt_pk_bf16_f32 v3, v4, v5
	ds_write_b64 v151, v[2:3] offset:26112
	global_load_dwordx4 v[0:3], v[0:1], off
	v_mov_b32_e32 v4, s81
	s_waitcnt vmcnt(0)
	v_cndmask_b32_e64 v4, v0, v4, s[64:65]
	v_cndmask_b32_e64 v0, v4, v0, s[66:67]
	v_cndmask_b32_e64 v1, 0, v1, s[66:67]
	v_cndmask_b32_e64 v2, v2, 0, s[68:69]
	v_cndmask_b32_e64 v3, v3, 0, s[70:71]
	v_cvt_pk_bf16_f32 v0, v0, v1
	v_cvt_pk_bf16_f32 v1, v2, v3
	ds_write_b64 v155, v[0:1]
	v_lshlrev_b32_e32 v0, 2, v56
	v_lshl_or_b32 v12, s0, 10, v0
	global_load_dwordx4 v[4:7], v12, s[76:77] offset:16
	global_load_dwordx4 v[0:3], v12, s[76:77]
	global_load_dwordx4 v[8:11], v12, s[78:79] offset:16
	s_nop 0
	global_load_dwordx4 v[12:15], v12, s[78:79]
	s_nop 0
	global_load_dword v84, v16, s[82:83]
	global_load_dword v86, v16, s[82:83] offset:64
	global_load_dword v88, v16, s[82:83] offset:128
	global_load_dword v90, v16, s[82:83] offset:192

; #define PG8_STAGE(bufoff, gbase, voff) do { const unsigned long long gb_ = (unsigned long long)(gbase); _Pragma("unroll") for (int _i = 0; _i < 2; ++_i) { unsigned keep_; \
;         asm volatile("s_mov_b32 m0, %2\n\ts_nop 0\n\tglobal_load_lds_dwordx4 %0, %1" : : "v"((voff)[_i]), "s"(gb_), "s"((unsigned)(size_t)(lds + (bufoff) + ldsw + _i * 8192)) : "memory", "m0"); (void)keep_; } } while (0)
; #define PG8_WAIT_V(n) asm volatile("s_waitcnt vmcnt(" #n ")" ::: "memory")
; #define PG8_BAR __builtin_amdgcn_s_barrier()
; template <class Epi, class Sched, bool ALIGN_EPI = false, bool SP2 = false>
; __device__ __forceinline__ void gemm_phase(PG8_LAS unsigned char* lds, const Gemm g, const Sched& S, const Epi& E) {
;     ...
;     for (int i = 0; i < 2; ++i) { int R, C; stage_rc(tid * 16 + i * 8192, R, C); const int Rb = Epi::PERM ? ((R & ~31) + perm32(R & 31)) : R;
;         voffA[i] = (unsigned)(R * g.lda + C) * 2u; voffB[i] = (unsigned)(Rb * K + C) * 2u; }
;     const size_t kstep = (size_t)(BK * 2);
;     const size_t hstepA = (size_t)HALF * g.lda * 2, hstepB = (size_t)HALF * K * 2;
;     const size_t tstepA = g.a_tstep ? g.a_tstep : 2 * hstepA, tstepB = 2 * hstepB;
;     const unsigned ldsw = (unsigned)wid * 1024u;
;     const int aoff = lds_byte(wr * 64 + fr, fq * 8), boff = lds_byte(wc * 32 + fr, fq * 8);
;     ...
;         PG8_STAGE(PG8_SB(0, 0), cB, voffB); PG8_STAGE(PG8_SB(0, 1), cB + hstepB, voffB); PG8_STAGE(PG8_SA(0, 0), cA, voffA); PG8_STAGE(PG8_SA(0, 1), cA + hstepA, voffA);
;         if (wr == 1) PG8_BAR;
;         PG8_WAIT_V(2); PG8_BAR;
;         PG8_STAGE(PG8_SB(1, 0), cB + kstep, voffB); PG8_STAGE(PG8_SA(1, 0), cA + kstep, voffA); PG8_STAGE(PG8_SB(1, 1), cB + hstepB + kstep, voffB);
;         PG8_WAIT_V(6); PG8_BAR;
.LBB0_1624:
	v_and_b32_e32 v1, 15, v200
	v_lshlrev_b32_e32 v2, 1, v0
	v_lshlrev_b32_e32 v4, 2, v200
	s_lshl_b32 s9, s1, 6
	v_lshl_or_b32 v3, v1, 6, v2
	s_lshl_b32 s1, s1, 13
	v_and_b32_e32 v4, 32, v4
	s_lshl_b32 s0, s0, 5
	v_bitop3_b32 v5, v3, s1, v4 bitop3:0xde
	s_and_b32 s26, s0, 0x60
	v_lshlrev_b32_e32 v3, 6, v200
	s_movk_i32 s0, 0x3c0
	v_and_or_b32 v2, v3, s0, v2
	s_lshl_b32 s0, s26, 7
	v_bitop3_b32 v4, s0, v2, v4 bitop3:0xf6
	v_mov_b32_e32 v2, 0x160000
	v_readlane_b32 s0, v254, 19
	v_mov_b32_e32 v145, 0
	s_nop 1
	v_mul_u32_u24_e32 v2, s0, v2
	v_cndmask_b32_e64 v2, v2, 0, s[24:25]
	v_lshlrev_b32_e32 v144, 1, v2
	v_lshl_add_u64 v[2:3], s[74:75], 0, v[144:145]
	s_mov_b64 s[0:1], 0xe000000
	v_lshl_add_u64 v[146:147], v[2:3], 0, s[0:1]
	s_add_u32 s0, s40, 0x80
	s_addc_u32 s1, s41, 0
	s_add_i32 s62, s39, 0x18000
	s_mov_b32 m0, s62
	s_nop 0
	global_load_lds_dwordx4 v161, s[0:1]
	s_add_i32 s63, s39, 0x1a000
	s_mov_b32 m0, s63
	s_nop 0
	global_load_lds_dwordx4 v169, s[0:1]
	s_add_u32 s0, s42, 0x80
	s_addc_u32 s1, s43, 0
	s_add_i32 s64, s39, 0x8000
	s_mov_b32 m0, s64
	s_nop 0
	global_load_lds_dwordx4 v149, s[0:1]
	s_add_i32 s65, s39, 0xa000
	s_mov_b32 m0, s65
	s_nop 0
	global_load_lds_dwordx4 v167, s[0:1]
	s_add_u32 s0, s40, 0x80080
	s_addc_u32 s1, s41, 0
	s_add_i32 s66, s39, 0x1c000
	s_mov_b32 m0, s66
	s_nop 0
	global_load_lds_dwordx4 v161, s[0:1]
	s_add_i32 s67, s39, 0x1e000
	s_add_i32 s68, s39, 0xc000
	s_mov_b32 m0, s67
	s_nop 0
	global_load_lds_dwordx4 v169, s[0:1]
	s_cmp_eq_u64 s[22:23], 0
	s_cbranch_scc1 .Lstag_skip_5
	s_barrier

; __device__ __forceinline__ unsigned pk2(float lo, float hi) { return f2bf(lo) | (f2bf(hi) << 16); }
; __device__ __forceinline__ float bflo(unsigned w) { return __uint_as_float(w << 16); }
; __device__ __forceinline__ float bfhi(unsigned w) { return __uint_as_float(w & 0xffff0000u); }
; __device__ __forceinline__ void attn_phase(LAS unsigned char* lds, const bf16* QKV, bf16* O, const float* rope, const float* sinks) {
;     ...
;         { if (half == 0) {
;               const float cs[8] = {kr[0][0], kr[0][2], kr[1][0], kr[1][2], kr[2][0], kr[2][2], kr[3][0], kr[3][2]}, sn[8] = {kr[0][1], kr[0][3], kr[1][1], kr[1][3], kr[2][1], kr[2][3], kr[3][1], kr[3][3]};
;               float x1[8], x2[8];
; #pragma unroll
;               for (int e = 0; e < 4; ++e) { x1[2 * e] = bflo(kw[0][e]); x1[2 * e + 1] = bfhi(kw[0][e]); x2[2 * e] = bflo(kw[1][e]); x2[2 * e + 1] = bfhi(kw[1][e]); }
; #pragma unroll
;               for (int e = 0; e < 4; ++e) { kw[0][e] = pk2(x1[2 * e] * cs[2 * e] - x2[2 * e] * sn[2 * e], x1[2 * e + 1] * cs[2 * e + 1] - x2[2 * e + 1] * sn[2 * e + 1]);
;                                             kw[1][e] = pk2(x2[2 * e] * cs[2 * e] + x1[2 * e] * sn[2 * e], x2[2 * e + 1] * cs[2 * e + 1] + x1[2 * e + 1] * sn[2 * e + 1]); } }
.LBB0_1741:
	s_and_saveexec_b64 s[14:15], s[6:7]
	s_cbranch_execz .LBB0_1743
	v_lshlrev_b32_e32 v53, 16, v5
	v_lshlrev_b32_e32 v52, 16, v4
	s_waitcnt vmcnt(1)
	v_lshlrev_b32_e32 v45, 16, v29
	v_lshlrev_b32_e32 v44, 16, v28
	v_and_b32_e32 v55, 0xffff0000, v5
	v_and_b32_e32 v54, 0xffff0000, v4
	v_pk_mul_f32 v[4:5], v[48:49], v[52:53]
	v_pk_mul_f32 v[52:53], v[40:41], v[52:53]
	v_and_b32_e32 v29, 0xffff0000, v29
	v_and_b32_e32 v28, 0xffff0000, v28
	v_pk_fma_f32 v[4:5], v[40:41], v[44:45], v[4:5]
	v_pk_mul_f32 v[56:57], v[50:51], v[54:55]
	v_pk_fma_f32 v[44:45], v[48:49], v[44:45], v[52:53] neg_lo:[0,0,1] neg_hi:[0,0,1]
	v_pk_mul_f32 v[52:53], v[42:43], v[54:55]
	v_pk_fma_f32 v[56:57], v[42:43], v[28:29], v[56:57]
	v_pk_fma_f32 v[28:29], v[50:51], v[28:29], v[52:53] neg_lo:[0,0,1] neg_hi:[0,0,1]
	v_cvt_pk_bf16_f32 v29, v45, v29
	v_and_b32_e32 v45, 0xffff0000, v30
	v_lshlrev_b32_e32 v52, 16, v6
	v_mov_b32_e32 v53, v45
	v_and_b32_e32 v55, 0xffff0000, v6
	v_and_b32_e32 v54, 16, v30
	v_cvt_pk_bf16_f32 v5, v5, v57
	v_cvt_pk_bf16_f32 v4, v4, v56
	v_cvt_pk_bf16_f32 v28, v44, v28
	v_and_b32_e32 v44, 16, v6
	v_lshlrev_b32_e32 v56, 16, v30
	v_mov_b32_e32 v57, v55
	v_pk_mov_b32 v[54:55], v[54:55], v[52:53] op_sel:[1,0]
	v_pk_mov_b32 v[44:45], v[44:45], v[56:57] op_sel:[1,0]
	v_pk_mul_f32 v[54:55], v[8:9], v[54:55]
	s_nop 0
	v_pk_fma_f32 v[44:45], v[46:47], v[44:45], v[54:55] neg_lo:[0,0,1] neg_hi:[0,0,1]
	v_mov_b32_e32 v54, v47
	v_and_b32_sdwa v6, v45, v122 dst_sel:DWORD dst_unused:UNUSED_PAD src0_sel:WORD_1 src1_sel:DWORD
	v_and_b32_sdwa v30, v44, v122 dst_sel:DWORD dst_unused:UNUSED_PAD src0_sel:WORD_1 src1_sel:DWORD
	v_mov_b32_e32 v55, v8
	v_add3_u32 v30, v44, v30, s39
	v_add3_u32 v6, v45, v6, s39
	v_mov_b32_e32 v44, v9
	v_mov_b32_e32 v45, v46
	v_pk_mul_f32 v[52:53], v[54:55], v[52:53]
	v_lshrrev_b32_e32 v6, 16, v6
	v_pk_fma_f32 v[44:45], v[44:45], v[56:57], v[52:53]
	v_and_or_b32 v30, v30, s38, v6
	v_and_b32_e32 v52, 0xffff0000, v7
	v_lshlrev_b32_e32 v53, 16, v7
	v_cvt_pk_bf16_f32 v6, v44, v45
	v_and_b32_e32 v44, 0xffff0000, v31
	v_lshlrev_b32_e32 v45, 16, v31
	v_pk_mul_f32 v[54:55], v[32:33], v[52:53]
	v_pk_mul_f32 v[52:53], v[10:11], v[52:53]
	v_pk_fma_f32 v[54:55], v[10:11], v[44:45], v[54:55] neg_lo:[0,0,1] neg_hi:[0,0,1]
	v_pk_fma_f32 v[44:45], v[32:33], v[44:45], v[52:53]
	v_cvt_pk_bf16_f32 v31, v55, v54
	v_cvt_pk_bf16_f32 v7, v45, v44

; #define LAS __attribute__((address_space(3)))
; __device__ __forceinline__ unsigned pk2(float lo, float hi) { return f2bf(lo) | (f2bf(hi) << 16); }
; __device__ __forceinline__ float bflo(unsigned w) { return __uint_as_float(w << 16); }
; __device__ __forceinline__ float bfhi(unsigned w) { return __uint_as_float(w & 0xffff0000u); }
; __device__ __forceinline__ void attn_phase(LAS unsigned char* lds, const bf16* QKV, bf16* O, const float* rope, const float* sinks) {
;     ...
;         ATT_LOAD_Q(0);
;         for (int a = 0; a < 8; ++a) {
;             const int qi = a * 16 + fr; const size_t qrow = qrow0 + a * 16;
;             bf16x8 qf[2];
;             { u32x4 w0 = qw0; const u32x4 w1 = qw1;
;               const float cs[8] = {qr[0][0], qr[0][2], qr[1][0], qr[1][2], qr[2][0], qr[2][2], qr[3][0], qr[3][2]}, sn[8] = {qr[0][1], qr[0][3], qr[1][1], qr[1][3], qr[2][1], qr[2][3], qr[3][1], qr[3][3]};
;               u32x4 pw; pw.x = __shfl_xor(w0.x, 16); pw.y = __shfl_xor(w0.y, 16); pw.z = __shfl_xor(w0.z, 16); pw.w = __shfl_xor(w0.w, 16);
;               const float sg = fq == 0 ? -1.f : 1.f;
;               u32x4 rw;
; #pragma unroll
;               for (int e = 0; e < 4; ++e) { const float xa = bflo(w0[e]), xb = bfhi(w0[e]), pa = bflo(pw[e]), pb = bfhi(pw[e]);
;                   rw[e] = pk2(xa * cs[2 * e] + sg * pa * sn[2 * e], xb * cs[2 * e + 1] + sg * pb * sn[2 * e + 1]); }
;               if (fq < 2) w0 = rw;
;               qf[0] = __builtin_bit_cast(bf16x8, w0); qf[1] = __builtin_bit_cast(bf16x8, w1); }
;             if (a < 7) ATT_LOAD_Q(a + 1);
;             f32x4 sc[10];
; #pragma unroll
;             for (int j = 0; j < 10; ++j) { const LAS bf16* kp = Kl + ((a + j) * 16 + fr) * KP + fq * 8;
;                 f32x4 z = (f32x4){0.f, 0.f, 0.f, 0.f};
;                 z = __builtin_amdgcn_mfma_f32_16x16x32_bf16(*(const LAS bf16x8*)kp, qf[0], z, 0, 0, 0);
;                 z = __builtin_amdgcn_mfma_f32_16x16x32_bf16(*(const LAS bf16x8*)(kp + 32), qf[1], z, 0, 0, 0);
;                 sc[j] = z; }
.LBB0_1748:
	s_waitcnt lgkmcnt(2)
	v_lshlrev_b32_e32 v133, 16, v127
	v_lshlrev_b32_e32 v132, 16, v126
	v_and_b32_e32 v127, 0xffff0000, v127
	v_and_b32_e32 v126, 0xffff0000, v126
	v_mov_b32_e32 v135, v92
	v_mov_b32_e32 v92, v97
	v_mov_b32_e32 v97, v94
	v_pk_mul_f32 v[126:127], v[104:105], v[126:127]
	v_mov_b32_e32 v94, v99
	v_and_b32_e32 v131, 0xffff0000, v81
	v_and_b32_e32 v130, 0xffff0000, v80
	v_mov_b32_e32 v134, v96
	v_pk_mul_f32 v[132:133], v[104:105], v[132:133]
	v_mov_b32_e32 v96, v98
	v_pk_mul_f32 v[94:95], v[94:95], v[126:127]
	s_waitcnt lgkmcnt(0)
	v_or_b32_e32 v165, s28, v34
	v_mad_u64_u32 v[166:167], s[100:101], v165, s42, v[106:107]
	ds_read_b128 v[168:171], v166 offset:0
	ds_read_b128 v[172:175], v166 offset:64
	ds_read_b128 v[176:179], v166 offset:2304
	ds_read_b128 v[180:183], v166 offset:2368
	ds_read_b128 v[184:187], v166 offset:4608
	ds_read_b128 v[188:191], v166 offset:4672
	ds_read_b128 v[192:195], v166 offset:6912
	ds_read_b128 v[196:199], v166 offset:6976
	ds_read_b128 v[202:205], v166 offset:9216
	ds_read_b128 v[206:209], v166 offset:9280
	ds_read_b128 v[210:213], v166 offset:11520
	ds_read_b128 v[214:217], v166 offset:11584
	ds_read_b128 v[218:221], v166 offset:13824
	ds_read_b128 v[222:225], v166 offset:13888
	ds_read_b128 v[226:229], v166 offset:16128
	ds_read_b128 v[230:233], v166 offset:16192
	ds_read_b128 v[234:237], v166 offset:18432
	ds_read_b128 v[238:241], v166 offset:18496
	ds_read_b128 v[242:245], v166 offset:20736
	ds_read_b128 v[246:249], v166 offset:20800
	v_lshlrev_b32_e32 v127, 16, v125
	v_lshlrev_b32_e32 v126, 16, v115
	v_lshlrev_b32_e32 v129, 16, v81
	v_lshlrev_b32_e32 v128, 16, v80
	v_pk_mul_f32 v[92:93], v[92:93], v[132:133]
	v_pk_fma_f32 v[94:95], v[96:97], v[130:131], v[94:95]
	v_mov_b32_e32 v131, v84
	v_pk_mul_f32 v[126:127], v[104:105], v[126:127]
	v_mov_b32_e32 v84, v89
	v_pk_fma_f32 v[92:93], v[134:135], v[128:129], v[92:93]
	v_lshlrev_b32_e32 v97, 16, v83
	v_lshlrev_b32_e32 v96, 16, v82
	v_and_b32_e32 v129, 0xffff0000, v125
	v_and_b32_e32 v128, 0xffff0000, v115
	v_mov_b32_e32 v130, v88
	v_pk_mul_f32 v[84:85], v[84:85], v[126:127]
	v_mov_b32_e32 v89, v86
	v_pk_fma_f32 v[84:85], v[130:131], v[96:97], v[84:85]
	v_pk_mul_f32 v[96:97], v[104:105], v[128:129]
	v_mov_b32_e32 v86, v91
	v_and_b32_e32 v99, 0xffff0000, v83
	v_and_b32_e32 v98, 0xffff0000, v82
	v_mov_b32_e32 v88, v90
	v_pk_mul_f32 v[86:87], v[86:87], v[96:97]
	v_or_b32_e32 v113, s28, v34
	v_pk_fma_f32 v[86:87], v[88:89], v[98:99], v[86:87]
	v_cvt_pk_bf16_f32 v88, v92, v94
	v_cvt_pk_bf16_f32 v89, v93, v95
	v_cvt_pk_bf16_f32 v90, v84, v86
	v_cvt_pk_bf16_f32 v91, v85, v87
	v_cndmask_b32_e64 v95, v83, v91, s[8:9]
	v_cndmask_b32_e64 v94, v82, v90, s[8:9]
	v_cndmask_b32_e64 v93, v81, v89, s[8:9]
	v_cndmask_b32_e64 v92, v80, v88, s[8:9]
	s_add_i32 s45, s50, 1
	s_lshl_b32 s54, s45, 4
	v_or_b32_e32 v88, s54, v34
	v_mad_u64_u32 v[126:127], s[18:19], v88, s42, v[106:107]
	s_waitcnt lgkmcnt(15)
	v_mfma_f32_16x16x32_bf16 v[84:87], v[168:171], v[92:95], 0
	s_add_i32 s49, s28, 32
	s_add_i32 s56, s28, 48
	s_waitcnt lgkmcnt(15)
	v_mfma_f32_16x16x32_bf16 v[96:99], v[172:175], v[76:79], v[84:87]
	s_add_i32 s48, s28, 64
	s_add_i32 s53, s28, 0x50
	s_waitcnt lgkmcnt(15)
	v_mfma_f32_16x16x32_bf16 v[84:87], v[176:179], v[92:95], 0
	v_or_b32_e32 v88, s56, v34
	v_mad_u64_u32 v[134:135], s[18:19], v88, s42, v[106:107]
	s_waitcnt lgkmcnt(15)
	v_mfma_f32_16x16x32_bf16 v[126:129], v[180:183], v[76:79], v[84:87]
	v_or_b32_e32 v80, s49, v34
	s_add_i32 s47, s28, 0x60
	s_add_i32 s52, s28, 0x70
	s_nop 0
	v_mad_u64_u32 v[84:85], s[18:19], v80, s42, v[106:107]
	s_waitcnt lgkmcnt(15)
	v_mfma_f32_16x16x32_bf16 v[80:83], v[184:187], v[92:95], 0
	s_add_i32 s46, s28, 0x80
	s_add_i32 s51, s28, 0x90
	s_waitcnt lgkmcnt(14)
	v_mfma_f32_16x16x32_bf16 v[130:133], v[188:191], v[76:79], v[80:83]
	v_or_b32_e32 v115, s51, v34
	v_mad_u64_u32 v[154:155], s[18:19], v115, s42, v[106:107]
	s_nop 0
	s_waitcnt lgkmcnt(13)
	v_mfma_f32_16x16x32_bf16 v[84:87], v[192:195], v[92:95], 0
	v_or_b32_e32 v88, s53, v34
	v_mad_u64_u32 v[142:143], s[18:19], v88, s42, v[106:107]
	s_waitcnt lgkmcnt(12)
	v_mfma_f32_16x16x32_bf16 v[134:137], v[196:199], v[76:79], v[84:87]
	v_or_b32_e32 v80, s48, v34
	s_nop 2
	v_mad_u64_u32 v[84:85], s[18:19], v80, s42, v[106:107]
	s_waitcnt lgkmcnt(11)
	v_mfma_f32_16x16x32_bf16 v[80:83], v[202:205], v[92:95], 0
	v_mul_f32_e32 v115, 0x3e000000, v127
	v_mul_f32_e32 v127, 0x3e000000, v130
	s_waitcnt lgkmcnt(10)
	v_mfma_f32_16x16x32_bf16 v[138:141], v[206:209], v[76:79], v[80:83]
	v_or_b32_e32 v130, s56, v108
	s_nop 1
	s_waitcnt lgkmcnt(9)
	v_mfma_f32_16x16x32_bf16 v[84:87], v[210:213], v[92:95], 0
	v_or_b32_e32 v88, s52, v34
	v_mad_u64_u32 v[150:151], s[18:19], v88, s42, v[106:107]
	s_waitcnt lgkmcnt(8)
	v_mfma_f32_16x16x32_bf16 v[142:145], v[214:217], v[76:79], v[84:87]
	v_or_b32_e32 v80, s47, v34
	s_nop 2
	v_mad_u64_u32 v[84:85], s[18:19], v80, s42, v[106:107]
	s_waitcnt lgkmcnt(7)
	v_mfma_f32_16x16x32_bf16 v[80:83], v[218:221], v[92:95], 0
	s_waitcnt lgkmcnt(6)
	v_mfma_f32_16x16x32_bf16 v[88:91], v[222:225], v[76:79], v[80:83]
	s_nop 4
	s_waitcnt lgkmcnt(5)
	v_mfma_f32_16x16x32_bf16 v[84:87], v[226:229], v[92:95], 0
	s_nop 0
	v_mul_f32_e32 v88, 0x3e000000, v88
	v_mul_f32_e32 v89, 0x3e000000, v89
	v_mul_f32_e32 v90, 0x3e000000, v90
	s_waitcnt lgkmcnt(4)
	v_mfma_f32_16x16x32_bf16 v[84:87], v[230:233], v[76:79], v[84:87]
	v_or_b32_e32 v80, s46, v34
	v_mad_u64_u32 v[146:147], s[18:19], v80, s42, v[106:107]
	s_waitcnt lgkmcnt(3)
	v_mfma_f32_16x16x32_bf16 v[80:83], v[234:237], v[92:95], 0
	v_mul_f32_e32 v91, 0x3e000000, v91
	s_nop 2
	v_mul_f32_e32 v84, 0x3e000000, v84
	s_waitcnt lgkmcnt(2)
; #define LAS __attribute__((address_space(3)))
; __device__ __forceinline__ void attn_phase(LAS unsigned char* lds, const bf16* QKV, bf16* O, const float* rope, const float* sinks) {
;     ...
;             for (int j = 0; j < 10; ++j) { const LAS bf16* kp = Kl + ((a + j) * 16 + fr) * KP + fq * 8;
;                 f32x4 z = (f32x4){0.f, 0.f, 0.f, 0.f};
;                 z = __builtin_amdgcn_mfma_f32_16x16x32_bf16(*(const LAS bf16x8*)kp, qf[0], z, 0, 0, 0);
;                 z = __builtin_amdgcn_mfma_f32_16x16x32_bf16(*(const LAS bf16x8*)(kp + 32), qf[1], z, 0, 0, 0);
;                 sc[j] = z; }
;             const int qpos = 128 + qi; float mx = -INFINITY;
; #pragma unroll
;             for (int j = 0; j < 10; ++j)
; #pragma unroll
;                 for (int e = 0; e < 4; ++e) { const int kpos = (a + j) * 16 + 4 * fq + e; const bool valid = (kpos <= qpos) && (kpos > qpos - 128) && (nb > 0 || kpos >= 128);
;                     const float sv = valid ? sc[j][e] * 0.125f : -INFINITY; sc[j][e] = sv; mx = fmaxf(mx, sv); }
	v_mfma_f32_16x16x32_bf16 v[80:83], v[238:241], v[76:79], v[80:83]
	v_mul_f32_e32 v85, 0x3e000000, v85
	v_mul_f32_e32 v86, 0x3e000000, v86
	s_waitcnt lgkmcnt(1)
	v_mfma_f32_16x16x32_bf16 v[92:95], v[242:245], v[92:95], 0
	v_mul_f32_e32 v87, 0x3e000000, v87
	s_nop 1
	s_nop 0
	v_mul_f32_e32 v80, 0x3e000000, v80
	v_mul_f32_e32 v82, 0x3e000000, v82
	s_waitcnt lgkmcnt(0)
	v_mfma_f32_16x16x32_bf16 v[76:79], v[246:249], v[76:79], v[92:95]
	s_nop 2
	v_or_b32_e32 v93, s28, v108
	v_mul_f32_e32 v95, 0x3e000000, v97
	v_or_b32_e32 v97, 2, v93
	v_cmp_gt_u32_e32 vcc, v97, v113
	v_mul_f32_e32 v97, 0x3e000000, v98
	s_and_b64 vcc, s[36:37], vcc
	v_or_b32_e32 v93, 3, v93
	v_cndmask_b32_e32 v97, v124, v97, vcc
	v_cmp_gt_u32_e32 vcc, v93, v113
	v_or_b32_e32 v92, 0x80, v113
	v_mul_f32_e32 v93, 0x3e000000, v99
	s_and_b64 vcc, s[36:37], vcc
	v_or_b32_e32 v98, s54, v108
	v_cndmask_b32_e32 v93, v124, v93, vcc
	v_cmp_le_u32_e32 vcc, v98, v92
	v_cmp_gt_u32_e64 s[18:19], v98, v113
	s_and_b64 s[18:19], vcc, s[18:19]
	s_cmp_gt_u32 s50, 6
	s_cselect_b64 s[54:55], -1, 0
	s_or_b64 s[54:55], s[36:37], s[54:55]
	v_mul_f32_e32 v99, 0x3e000000, v126
	s_and_b64 vcc, s[18:19], s[54:55]
	v_cndmask_b32_e32 v99, v124, v99, vcc
	v_cmp_lt_u32_e32 vcc, v98, v92
	v_cmp_ge_u32_e64 s[18:19], v98, v113
	s_and_b64 s[18:19], vcc, s[18:19]
	s_and_b64 vcc, s[18:19], s[54:55]
	v_or_b32_e32 v125, 2, v98
	v_cndmask_b32_e32 v115, v124, v115, vcc
	v_cmp_le_u32_e32 vcc, v125, v92
	v_cmp_gt_u32_e64 s[18:19], v125, v113
	s_and_b64 s[18:19], vcc, s[18:19]
	v_mul_f32_e32 v125, 0x3e000000, v128
	s_and_b64 vcc, s[18:19], s[54:55]
	v_or_b32_e32 v98, 3, v98
	v_cndmask_b32_e32 v125, v124, v125, vcc
	v_cmp_le_u32_e32 vcc, v98, v92
	v_cmp_gt_u32_e64 s[18:19], v98, v113
	s_and_b64 s[18:19], vcc, s[18:19]
	v_mul_f32_e32 v98, 0x3e000000, v129
	s_and_b64 vcc, s[18:19], s[54:55]
	v_or_b32_e32 v126, s49, v108
	v_cndmask_b32_e32 v98, v124, v98, vcc
	v_cmp_le_u32_e32 vcc, v126, v92
	v_cmp_gt_u32_e64 s[18:19], v126, v113
	s_and_b64 s[18:19], vcc, s[18:19]
	s_cmpk_gt_u32 s28, 0x5f
	s_cselect_b64 s[54:55], -1, 0
	s_or_b64 s[54:55], s[36:37], s[54:55]
	s_and_b64 vcc, s[54:55], s[18:19]
	v_cndmask_b32_e32 v127, v124, v127, vcc
	v_cmp_lt_u32_e32 vcc, v126, v92
	v_cmp_ge_u32_e64 s[18:19], v126, v113
	s_and_b64 s[18:19], vcc, s[18:19]
	v_mul_f32_e32 v128, 0x3e000000, v131
	s_and_b64 vcc, s[54:55], s[18:19]
	v_or_b32_e32 v129, 2, v126
	v_cndmask_b32_e32 v128, v124, v128, vcc
	v_cmp_le_u32_e32 vcc, v129, v92
	v_cmp_gt_u32_e64 s[18:19], v129, v113
	s_and_b64 s[18:19], vcc, s[18:19]
	v_mul_f32_e32 v129, 0x3e000000, v132
	s_and_b64 vcc, s[54:55], s[18:19]
	v_or_b32_e32 v126, 3, v126
	v_cndmask_b32_e32 v129, v124, v129, vcc
	v_cmp_le_u32_e32 vcc, v126, v92
	v_cmp_gt_u32_e64 s[18:19], v126, v113
	s_and_b64 s[18:19], vcc, s[18:19]
	v_mul_f32_e32 v126, 0x3e000000, v133
	s_and_b64 vcc, s[54:55], s[18:19]
	v_cndmask_b32_e32 v126, v124, v126, vcc
	v_cmp_le_u32_e32 vcc, v130, v92
	v_cmp_gt_u32_e64 s[18:19], v130, v113
	s_and_b64 s[18:19], vcc, s[18:19]
	s_cmpk_gt_u32 s28, 0x4f
	s_cselect_b64 s[54:55], -1, 0
	s_or_b64 s[54:55], s[36:37], s[54:55]
	v_mul_f32_e32 v131, 0x3e000000, v134
	s_and_b64 vcc, s[54:55], s[18:19]
	v_cndmask_b32_e32 v131, v124, v131, vcc
	v_cmp_lt_u32_e32 vcc, v130, v92
	v_cmp_ge_u32_e64 s[18:19], v130, v113
	s_and_b64 s[18:19], vcc, s[18:19]
	v_mul_f32_e32 v132, 0x3e000000, v135
	s_and_b64 vcc, s[54:55], s[18:19]
	v_or_b32_e32 v133, 2, v130
	v_cndmask_b32_e32 v132, v124, v132, vcc
	v_cmp_le_u32_e32 vcc, v133, v92
	v_cmp_gt_u32_e64 s[18:19], v133, v113
	s_and_b64 s[18:19], vcc, s[18:19]
	v_mul_f32_e32 v133, 0x3e000000, v136
	s_and_b64 vcc, s[54:55], s[18:19]
	v_or_b32_e32 v130, 3, v130
	v_cndmask_b32_e32 v133, v124, v133, vcc
	v_cmp_le_u32_e32 vcc, v130, v92
	v_cmp_gt_u32_e64 s[18:19], v130, v113
	s_and_b64 s[18:19], vcc, s[18:19]
	v_mul_f32_e32 v130, 0x3e000000, v137
	s_and_b64 vcc, s[54:55], s[18:19]
	v_or_b32_e32 v134, s48, v108
	v_cndmask_b32_e32 v130, v124, v130, vcc
	v_cmp_le_u32_e32 vcc, v134, v92
	v_cmp_gt_u32_e64 s[18:19], v134, v113
	s_and_b64 s[18:19], vcc, s[18:19]
	s_cmp_gt_u32 s28, 63
	s_cselect_b64 s[54:55], -1, 0
	s_or_b64 s[54:55], s[36:37], s[54:55]
	v_mul_f32_e32 v135, 0x3e000000, v138
	s_and_b64 vcc, s[54:55], s[18:19]
	v_cndmask_b32_e32 v135, v124, v135, vcc
	v_cmp_lt_u32_e32 vcc, v134, v92
	v_cmp_ge_u32_e64 s[18:19], v134, v113
	s_and_b64 s[18:19], vcc, s[18:19]
	v_mul_f32_e32 v136, 0x3e000000, v139
	s_and_b64 vcc, s[54:55], s[18:19]
	v_or_b32_e32 v137, 2, v134
	v_cndmask_b32_e32 v136, v124, v136, vcc
	v_cmp_le_u32_e32 vcc, v137, v92
	v_cmp_gt_u32_e64 s[18:19], v137, v113
	s_and_b64 s[18:19], vcc, s[18:19]
	v_mul_f32_e32 v137, 0x3e000000, v140
	s_and_b64 vcc, s[54:55], s[18:19]
	v_or_b32_e32 v134, 3, v134
	v_cndmask_b32_e32 v137, v124, v137, vcc
	v_cmp_le_u32_e32 vcc, v134, v92
	v_cmp_gt_u32_e64 s[18:19], v134, v113
	s_and_b64 s[18:19], vcc, s[18:19]
	v_mul_f32_e32 v134, 0x3e000000, v141
	s_and_b64 vcc, s[54:55], s[18:19]
	v_or_b32_e32 v138, s53, v108
	v_cndmask_b32_e32 v134, v124, v134, vcc
	v_cmp_le_u32_e32 vcc, v138, v92
	v_cmp_gt_u32_e64 s[18:19], v138, v113
	s_and_b64 s[18:19], vcc, s[18:19]
	s_cmp_gt_u32 s28, 47
	s_cselect_b64 s[54:55], -1, 0
	s_or_b64 s[54:55], s[36:37], s[54:55]
	v_mul_f32_e32 v139, 0x3e000000, v142
	s_and_b64 vcc, s[54:55], s[18:19]
	v_cndmask_b32_e32 v139, v124, v139, vcc
	v_cmp_lt_u32_e32 vcc, v138, v92
	v_cmp_ge_u32_e64 s[18:19], v138, v113
	s_and_b64 s[18:19], vcc, s[18:19]
	v_mul_f32_e32 v140, 0x3e000000, v143
	s_and_b64 vcc, s[54:55], s[18:19]
	v_or_b32_e32 v141, 2, v138
	v_cndmask_b32_e32 v140, v124, v140, vcc
	v_cmp_le_u32_e32 vcc, v141, v92
; __device__ __forceinline__ void attn_phase(LAS unsigned char* lds, const bf16* QKV, bf16* O, const float* rope, const float* sinks) {
;     ...
;             const int qpos = 128 + qi; float mx = -INFINITY;
; #pragma unroll
;             for (int j = 0; j < 10; ++j)
; #pragma unroll
;                 for (int e = 0; e < 4; ++e) { const int kpos = (a + j) * 16 + 4 * fq + e; const bool valid = (kpos <= qpos) && (kpos > qpos - 128) && (nb > 0 || kpos >= 128);
;                     const float sv = valid ? sc[j][e] * 0.125f : -INFINITY; sc[j][e] = sv; mx = fmaxf(mx, sv); }
;             mx = fmaxf(mx, __shfl_xor(mx, 16)); mx = fmaxf(mx, __shfl_xor(mx, 32)); mx = fmaxf(mx, sink);
;             float l = 0.f;
; #pragma unroll
;             for (int j = 0; j < 10; ++j)
; #pragma unroll
;                 for (int e = 0; e < 4; ++e) { const float p = __expf(sc[j][e] - mx); sc[j][e] = p; l += p; }
;             l += __shfl_xor(l, 16); l += __shfl_xor(l, 32); l += __expf(sink - mx);
	v_cmp_gt_u32_e64 s[18:19], v141, v113
	s_and_b64 s[18:19], vcc, s[18:19]
	v_mul_f32_e32 v141, 0x3e000000, v144
	s_and_b64 vcc, s[54:55], s[18:19]
	v_or_b32_e32 v138, 3, v138
	v_cndmask_b32_e32 v141, v124, v141, vcc
	v_cmp_le_u32_e32 vcc, v138, v92
	v_cmp_gt_u32_e64 s[18:19], v138, v113
	s_and_b64 s[18:19], vcc, s[18:19]
	v_mul_f32_e32 v138, 0x3e000000, v145
	s_and_b64 vcc, s[54:55], s[18:19]
	v_or_b32_e32 v142, s47, v108
	v_cndmask_b32_e32 v138, v124, v138, vcc
	v_cmp_le_u32_e32 vcc, v142, v92
	v_cmp_gt_u32_e64 s[18:19], v142, v113
	s_and_b64 s[18:19], vcc, s[18:19]
	s_cmp_gt_u32 s28, 31
	s_cselect_b64 s[54:55], -1, 0
	s_or_b64 s[54:55], s[36:37], s[54:55]
	s_and_b64 vcc, s[54:55], s[18:19]
	v_cndmask_b32_e32 v88, v124, v88, vcc
	v_cmp_lt_u32_e32 vcc, v142, v92
	v_cmp_ge_u32_e64 s[18:19], v142, v113
	s_and_b64 s[18:19], vcc, s[18:19]
	s_and_b64 vcc, s[54:55], s[18:19]
	v_or_b32_e32 v143, 2, v142
	v_cndmask_b32_e32 v89, v124, v89, vcc
	v_cmp_le_u32_e32 vcc, v143, v92
	v_cmp_gt_u32_e64 s[18:19], v143, v113
	s_and_b64 s[18:19], vcc, s[18:19]
	s_and_b64 vcc, s[54:55], s[18:19]
	v_or_b32_e32 v142, 3, v142
	v_cndmask_b32_e32 v90, v124, v90, vcc
	v_cmp_le_u32_e32 vcc, v142, v92
	v_cmp_gt_u32_e64 s[18:19], v142, v113
	s_and_b64 s[18:19], vcc, s[18:19]
	s_and_b64 vcc, s[54:55], s[18:19]
	v_or_b32_e32 v142, s52, v108
	v_cndmask_b32_e32 v91, v124, v91, vcc
	v_cmp_le_u32_e32 vcc, v142, v92
	v_cmp_gt_u32_e64 s[18:19], v142, v113
	s_and_b64 s[18:19], vcc, s[18:19]
	v_mul_f32_e32 v94, 0x3e000000, v96
	s_cmp_lg_u32 s28, 0
	v_cndmask_b32_e64 v94, v124, v94, s[14:15]
	v_cndmask_b32_e64 v95, v124, v95, s[16:17]
	s_cselect_b64 s[52:53], -1, 0
	v_max3_f32 v96, v94, s43, v95
	s_or_b64 s[52:53], s[36:37], s[52:53]
	v_max3_f32 v96, v96, v97, v93
	s_and_b64 vcc, s[52:53], s[18:19]
	v_max3_f32 v96, v96, v99, v115
	v_cndmask_b32_e32 v84, v124, v84, vcc
	v_cmp_lt_u32_e32 vcc, v142, v92
	v_cmp_ge_u32_e64 s[18:19], v142, v113
	v_max3_f32 v96, v96, v125, v98
	s_and_b64 s[18:19], vcc, s[18:19]
	v_max3_f32 v96, v96, v127, v128
	s_and_b64 vcc, s[52:53], s[18:19]
	v_or_b32_e32 v143, 2, v142
	v_max3_f32 v96, v96, v129, v126
	v_cndmask_b32_e32 v85, v124, v85, vcc
	v_cmp_le_u32_e32 vcc, v143, v92
	v_cmp_gt_u32_e64 s[18:19], v143, v113
	v_max3_f32 v96, v96, v131, v132
	s_and_b64 s[18:19], vcc, s[18:19]
	v_max3_f32 v96, v96, v133, v130
	s_and_b64 vcc, s[52:53], s[18:19]
	v_or_b32_e32 v142, 3, v142
	v_max3_f32 v96, v96, v135, v136
	v_cndmask_b32_e32 v86, v124, v86, vcc
	v_cmp_le_u32_e32 vcc, v142, v92
	v_cmp_gt_u32_e64 s[18:19], v142, v113
	v_max3_f32 v96, v96, v137, v134
	s_and_b64 s[18:19], vcc, s[18:19]
	v_max3_f32 v96, v96, v139, v140
	s_and_b64 vcc, s[52:53], s[18:19]
	v_or_b32_e32 v113, s46, v108
	v_max3_f32 v96, v96, v141, v138
	v_cndmask_b32_e32 v87, v124, v87, vcc
	v_cmp_le_u32_e32 vcc, v113, v92
	v_max3_f32 v96, v96, v88, v89
	v_max3_f32 v96, v96, v90, v91
	v_cndmask_b32_e32 v142, v124, v80, vcc
	v_mul_f32_e32 v80, 0x3e000000, v81
	v_cmp_lt_u32_e32 vcc, v113, v92
	v_or_b32_e32 v81, 2, v113
	v_max3_f32 v96, v96, v84, v85
	v_cndmask_b32_e32 v143, v124, v80, vcc
	v_cmp_le_u32_e32 vcc, v81, v92
	v_or_b32_e32 v81, 3, v113
	v_max3_f32 v96, v96, v86, v87
	v_cndmask_b32_e32 v144, v124, v82, vcc
	v_mul_f32_e32 v82, 0x3e000000, v83
	v_cmp_le_u32_e32 vcc, v81, v92
	v_or_b32_e32 v81, s51, v108
	v_mul_f32_e32 v76, 0x3e000000, v76
	v_cndmask_b32_e32 v113, v124, v82, vcc
	v_cmp_le_u32_e32 vcc, v81, v92
	v_max3_f32 v80, v96, v142, v143
	v_max3_f32 v80, v80, v144, v113
	v_cndmask_b32_e32 v145, v124, v76, vcc
	v_mul_f32_e32 v76, 0x3e000000, v77
	v_cmp_lt_u32_e32 vcc, v81, v92
	v_mul_f32_e32 v78, 0x3e000000, v78
	v_mul_f32_e32 v79, 0x3e000000, v79
	v_cndmask_b32_e32 v77, v124, v76, vcc
	v_max3_f32 v76, v80, v145, v77
	v_or_b32_e32 v80, 2, v81
	v_cmp_le_u32_e32 vcc, v80, v92
	s_cmp_eq_u32 s45, 8
	s_mov_b32 s50, s45
	v_cndmask_b32_e32 v146, v124, v78, vcc
	v_or_b32_e32 v78, 3, v81
	v_cmp_le_u32_e32 vcc, v78, v92
	s_nop 1
	v_cndmask_b32_e32 v147, v124, v79, vcc
	v_max3_f32 v76, v76, v146, v147
	ds_bpermute_b32 v78, v111, v76
	s_waitcnt lgkmcnt(0)
	v_max_f32_e32 v78, v78, v78
	v_max_f32_e32 v76, v76, v78
	ds_bpermute_b32 v78, v120, v76
	s_waitcnt vmcnt(0) lgkmcnt(0)
	v_max3_f32 v76, v76, v78, v117
	v_sub_f32_e32 v79, v95, v76
	v_sub_f32_e32 v95, v127, v76
	v_mul_f32_e32 v95, 0x3fb8aa3b, v95
	v_sub_f32_e32 v78, v94, v76
	v_sub_f32_e32 v94, v98, v76
	v_exp_f32_e32 v98, v95
	v_sub_f32_e32 v95, v128, v76
	v_mul_f32_e32 v95, 0x3fb8aa3b, v95
	v_sub_f32_e32 v83, v99, v76
	v_exp_f32_e32 v99, v95
	v_sub_f32_e32 v95, v129, v76
	v_mul_f32_e32 v95, 0x3fb8aa3b, v95
	v_sub_f32_e32 v92, v115, v76
	v_exp_f32_e32 v115, v95
	v_sub_f32_e32 v95, v126, v76
	v_mul_f32_e32 v95, 0x3fb8aa3b, v95
	v_mul_f32_e32 v78, 0x3fb8aa3b, v78
	v_sub_f32_e32 v82, v93, v76
	v_sub_f32_e32 v93, v125, v76
	v_exp_f32_e32 v125, v95
	v_sub_f32_e32 v95, v131, v76
	v_exp_f32_e32 v78, v78
	v_mul_f32_e32 v79, 0x3fb8aa3b, v79
	v_sub_f32_e32 v80, v97, v76
	v_mul_f32_e32 v95, 0x3fb8aa3b, v95
	v_exp_f32_e32 v79, v79
	v_mul_f32_e32 v80, 0x3fb8aa3b, v80
	v_exp_f32_e32 v126, v95
	v_sub_f32_e32 v95, v132, v76
	v_exp_f32_e32 v80, v80
	v_mul_f32_e32 v82, 0x3fb8aa3b, v82
	v_mul_f32_e32 v95, 0x3fb8aa3b, v95
	v_exp_f32_e32 v82, v82
	v_mul_f32_e32 v83, 0x3fb8aa3b, v83
	v_exp_f32_e32 v127, v95
	v_sub_f32_e32 v95, v133, v76
	v_add_f32_e32 v81, 0, v78
	v_exp_f32_e32 v83, v83
	v_mul_f32_e32 v92, 0x3fb8aa3b, v92
	v_mul_f32_e32 v95, 0x3fb8aa3b, v95
	v_add_f32_e32 v81, v79, v81
	v_exp_f32_e32 v92, v92
	v_mul_f32_e32 v93, 0x3fb8aa3b, v93
	v_exp_f32_e32 v128, v95
	v_sub_f32_e32 v95, v130, v76
	v_add_f32_e32 v81, v80, v81
	v_exp_f32_e32 v93, v93
; #define LAS __attribute__((address_space(3)))
; __device__ __forceinline__ unsigned pk2(float lo, float hi) { return f2bf(lo) | (f2bf(hi) << 16); }
; __device__ __forceinline__ s16x4 tr_read(const LAS bf16* p) { return __builtin_bit_cast(s16x4, __builtin_amdgcn_ds_read_tr16_b64_v4i16((LAS s16x4*)p)); }
; __device__ __forceinline__ void attn_phase(LAS unsigned char* lds, const bf16* QKV, bf16* O, const float* rope, const float* sinks) {
;     ...
;             float l = 0.f;
; #pragma unroll
;             for (int j = 0; j < 10; ++j)
; #pragma unroll
;                 for (int e = 0; e < 4; ++e) { const float p = __expf(sc[j][e] - mx); sc[j][e] = p; l += p; }
;             l += __shfl_xor(l, 16); l += __shfl_xor(l, 32); l += __expf(sink - mx);
;             const float rl = 1.0f / l;
;             f32x4 oacc[4];
; #pragma unroll
;             for (int c = 0; c < 4; ++c) oacc[c] = (f32x4){0.f, 0.f, 0.f, 0.f};
; #pragma unroll
;             for (int j2 = 0; j2 < 5; ++j2) {
;                 u32x4 pwv; pwv.x = pk2(sc[2 * j2][0], sc[2 * j2][1]); pwv.y = pk2(sc[2 * j2][2], sc[2 * j2][3]); pwv.z = pk2(sc[2 * j2 + 1][0], sc[2 * j2 + 1][1]); pwv.w = pk2(sc[2 * j2 + 1][2], sc[2 * j2 + 1][3]);
;                 const bf16x8 pf = __builtin_bit_cast(bf16x8, pwv);
; #pragma unroll
;                 for (int c = 0; c < 4; ++c) { const LAS bf16* vp = Vl + ((a + 2 * j2) * 16 + 4 * fq + q4) * KP + 16 * c + 4 * p4;
;                     const s16x4 lo = tr_read(vp), hi = tr_read(vp + 16 * KP);
;                     const bf16x8 vf = (bf16x8){lo[0], lo[1], lo[2], lo[3], hi[0], hi[1], hi[2], hi[3]};
;                     oacc[c] = __builtin_amdgcn_mfma_f32_16x16x32_bf16(vf, pf, oacc[c], 0, 0, 0); }
	v_mul_f32_e32 v94, 0x3fb8aa3b, v94
	v_mul_f32_e32 v95, 0x3fb8aa3b, v95
	v_add_f32_e32 v81, v82, v81
	v_exp_f32_e32 v94, v94
	v_exp_f32_e32 v129, v95
	v_sub_f32_e32 v95, v135, v76
	v_add_f32_e32 v81, v83, v81
	v_mul_f32_e32 v95, 0x3fb8aa3b, v95
	v_add_f32_e32 v81, v92, v81
	v_exp_f32_e32 v148, v95
	v_sub_f32_e32 v95, v136, v76
	v_add_f32_e32 v81, v93, v81
	v_mul_f32_e32 v95, 0x3fb8aa3b, v95
	v_add_f32_e32 v81, v94, v81
	v_exp_f32_e32 v149, v95
	v_sub_f32_e32 v95, v137, v76
	v_add_f32_e32 v81, v98, v81
	v_mul_f32_e32 v95, 0x3fb8aa3b, v95
	v_add_f32_e32 v81, v99, v81
	v_exp_f32_e32 v150, v95
	v_sub_f32_e32 v95, v134, v76
	v_add_f32_e32 v81, v115, v81
	v_mul_f32_e32 v95, 0x3fb8aa3b, v95
	v_add_f32_e32 v81, v125, v81
	v_exp_f32_e32 v151, v95
	v_sub_f32_e32 v95, v139, v76
	v_add_f32_e32 v81, v126, v81
	v_mul_f32_e32 v95, 0x3fb8aa3b, v95
	v_add_f32_e32 v81, v127, v81
	v_exp_f32_e32 v152, v95
	v_sub_f32_e32 v95, v140, v76
	v_add_f32_e32 v81, v128, v81
	v_mul_f32_e32 v95, 0x3fb8aa3b, v95
	v_add_f32_e32 v81, v129, v81
	v_exp_f32_e32 v153, v95
	v_sub_f32_e32 v95, v141, v76
	v_sub_f32_e32 v88, v88, v76
	v_add_f32_e32 v81, v148, v81
	v_mul_f32_e32 v95, 0x3fb8aa3b, v95
	v_mul_f32_e32 v88, 0x3fb8aa3b, v88
	v_add_f32_e32 v81, v149, v81
	v_exp_f32_e32 v154, v95
	v_sub_f32_e32 v95, v138, v76
	v_exp_f32_e32 v156, v88
	v_sub_f32_e32 v88, v89, v76
	v_add_f32_e32 v81, v150, v81
	v_mul_f32_e32 v95, 0x3fb8aa3b, v95
	v_mul_f32_e32 v88, 0x3fb8aa3b, v88
	v_add_f32_e32 v81, v151, v81
	v_exp_f32_e32 v155, v95
	v_exp_f32_e32 v157, v88
	v_sub_f32_e32 v88, v90, v76
	v_add_f32_e32 v81, v152, v81
	v_mul_f32_e32 v88, 0x3fb8aa3b, v88
	v_sub_f32_e32 v84, v84, v76
	v_add_f32_e32 v81, v153, v81
	v_exp_f32_e32 v158, v88
	v_sub_f32_e32 v88, v91, v76
	v_mul_f32_e32 v84, 0x3fb8aa3b, v84
	v_add_f32_e32 v81, v154, v81
	v_mul_f32_e32 v88, 0x3fb8aa3b, v88
	v_exp_f32_e32 v160, v84
	v_sub_f32_e32 v84, v85, v76
	v_add_f32_e32 v81, v155, v81
	v_exp_f32_e32 v159, v88
	v_mul_f32_e32 v84, 0x3fb8aa3b, v84
	v_add_f32_e32 v81, v156, v81
	v_exp_f32_e32 v161, v84
	v_sub_f32_e32 v84, v86, v76
	v_add_f32_e32 v81, v157, v81
	v_mul_f32_e32 v84, 0x3fb8aa3b, v84
	v_add_f32_e32 v81, v158, v81
	v_exp_f32_e32 v162, v84
	v_add_f32_e32 v81, v159, v81
	v_add_f32_e32 v81, v160, v81
	v_add_f32_e32 v81, v161, v81
	v_bfe_u32 v85, v82, 16, 1
	v_bfe_u32 v86, v79, 16, 1
	v_add_f32_e32 v130, v162, v81
	v_sub_f32_e32 v81, v87, v76
	v_add3_u32 v86, v79, v86, s39
	v_add3_u32 v79, v82, v85, s39
	v_bfe_u32 v85, v80, 16, 1
	v_add3_u32 v80, v80, v85, s39
	v_mul_f32_e32 v81, 0x3fb8aa3b, v81
	v_bfe_u32 v84, v78, 16, 1
	v_lshrrev_b32_e32 v87, 16, v80
	v_exp_f32_e32 v163, v81
	v_add3_u32 v78, v78, v84, s39
	v_cvt_pk_bf16_f32 v80, v83, v92
	v_or_b32_e32 v82, s28, v121
	v_sub_f32_e32 v131, v142, v76
	v_lshrrev_b32_e32 v78, 16, v78
	v_mad_u64_u32 v[96:97], s[18:19], v82, s42, v[110:111]
	v_mul_f32_e32 v131, 0x3fb8aa3b, v131
	v_cvt_pk_bf16_f32 v81, v93, v94
	ds_read_b64_tr_b16 v[84:85], v96 offset:41472
	ds_read_b64_tr_b16 v[82:83], v96 offset:39168
	v_and_or_b32 v79, v79, s38, v87
	v_and_or_b32 v78, v86, s38, v78
	ds_read_b64_tr_b16 v[88:89], v96 offset:41504
	ds_read_b64_tr_b16 v[86:87], v96 offset:39200
	ds_read_b64_tr_b16 v[90:91], v96 offset:39232
	ds_read_b64_tr_b16 v[94:95], v96 offset:39264
	ds_read_b64_tr_b16 v[92:93], v96 offset:41536
	ds_read_b64_tr_b16 v[96:97], v96 offset:41568
	v_exp_f32_e32 v142, v131
	v_sub_f32_e32 v131, v143, v76
	v_mul_f32_e32 v131, 0x3fb8aa3b, v131
	v_exp_f32_e32 v143, v131
	v_add_f32_e32 v130, v163, v130
	s_waitcnt lgkmcnt(6)
	v_mfma_f32_16x16x32_bf16 v[82:85], v[82:85], v[78:81], 0
	v_add_f32_e32 v130, v142, v130
	v_add_f32_e32 v164, v143, v130
	v_sub_f32_e32 v77, v77, v76
	s_waitcnt lgkmcnt(4)
	v_mfma_f32_16x16x32_bf16 v[86:89], v[86:89], v[78:81], 0
	v_mul_f32_e32 v77, 0x3fb8aa3b, v77
	v_exp_f32_e32 v77, v77
	s_waitcnt lgkmcnt(1)
	v_mfma_f32_16x16x32_bf16 v[90:93], v[90:93], v[78:81], 0
	s_waitcnt lgkmcnt(0)
	v_mfma_f32_16x16x32_bf16 v[78:81], v[94:97], v[78:81], 0
	v_bfe_u32 v97, v99, 16, 1
	v_add3_u32 v130, v99, v97, s39
	v_bfe_u32 v97, v115, 16, 1
	v_bfe_u32 v96, v125, 16, 1
	v_add3_u32 v97, v115, v97, s39
	v_add3_u32 v125, v125, v96, s39
	v_bfe_u32 v96, v98, 16, 1
	v_lshrrev_b32_e32 v131, 16, v97
	v_add3_u32 v96, v98, v96, s39
	v_cvt_pk_bf16_f32 v97, v128, v129
	v_or_b32_e32 v94, s49, v121
	v_lshrrev_b32_e32 v115, 16, v96
	v_mad_u64_u32 v[98:99], s[18:19], v94, s42, v[110:111]
	v_cvt_pk_bf16_f32 v96, v126, v127
	ds_read_b64_tr_b16 v[128:129], v98 offset:41472
	ds_read_b64_tr_b16 v[126:127], v98 offset:39168
	v_and_or_b32 v95, v125, s38, v131
	v_and_or_b32 v94, v130, s38, v115
	ds_read_b64_tr_b16 v[132:133], v98 offset:41504
	ds_read_b64_tr_b16 v[130:131], v98 offset:39200
	ds_read_b64_tr_b16 v[134:135], v98 offset:39232
	ds_read_b64_tr_b16 v[138:139], v98 offset:39264
	ds_read_b64_tr_b16 v[136:137], v98 offset:41536
	ds_read_b64_tr_b16 v[140:141], v98 offset:41568
	v_sub_f32_e32 v98, v144, v76
	v_mul_f32_e32 v98, 0x3fb8aa3b, v98
	v_exp_f32_e32 v115, v98
	v_sub_f32_e32 v98, v113, v76
	s_waitcnt lgkmcnt(6)
	v_mfma_f32_16x16x32_bf16 v[82:85], v[126:129], v[94:97], v[82:85]
	v_mul_f32_e32 v98, 0x3fb8aa3b, v98
	v_exp_f32_e32 v113, v98
	v_sub_f32_e32 v98, v145, v76
	s_waitcnt lgkmcnt(4)
	v_mfma_f32_16x16x32_bf16 v[86:89], v[130:133], v[94:97], v[86:89]
	v_mul_f32_e32 v98, 0x3fb8aa3b, v98
	s_waitcnt lgkmcnt(1)
	v_mfma_f32_16x16x32_bf16 v[90:93], v[134:137], v[94:97], v[90:93]
	v_exp_f32_e32 v125, v98
	s_waitcnt lgkmcnt(0)
; #define LAS __attribute__((address_space(3)))
; __device__ __forceinline__ unsigned pk2(float lo, float hi) { return f2bf(lo) | (f2bf(hi) << 16); }
; __device__ __forceinline__ s16x4 tr_read(const LAS bf16* p) { return __builtin_bit_cast(s16x4, __builtin_amdgcn_ds_read_tr16_b64_v4i16((LAS s16x4*)p)); }
; __device__ __forceinline__ void attn_phase(LAS unsigned char* lds, const bf16* QKV, bf16* O, const float* rope, const float* sinks) {
;     ...
;             l += __shfl_xor(l, 16); l += __shfl_xor(l, 32); l += __expf(sink - mx);
;             const float rl = 1.0f / l;
;             f32x4 oacc[4];
; #pragma unroll
;             for (int c = 0; c < 4; ++c) oacc[c] = (f32x4){0.f, 0.f, 0.f, 0.f};
; #pragma unroll
;             for (int j2 = 0; j2 < 5; ++j2) {
;                 u32x4 pwv; pwv.x = pk2(sc[2 * j2][0], sc[2 * j2][1]); pwv.y = pk2(sc[2 * j2][2], sc[2 * j2][3]); pwv.z = pk2(sc[2 * j2 + 1][0], sc[2 * j2 + 1][1]); pwv.w = pk2(sc[2 * j2 + 1][2], sc[2 * j2 + 1][3]);
;                 const bf16x8 pf = __builtin_bit_cast(bf16x8, pwv);
; #pragma unroll
;                 for (int c = 0; c < 4; ++c) { const LAS bf16* vp = Vl + ((a + 2 * j2) * 16 + 4 * fq + q4) * KP + 16 * c + 4 * p4;
;                     const s16x4 lo = tr_read(vp), hi = tr_read(vp + 16 * KP);
;                     const bf16x8 vf = (bf16x8){lo[0], lo[1], lo[2], lo[3], hi[0], hi[1], hi[2], hi[3]};
;                     oacc[c] = __builtin_amdgcn_mfma_f32_16x16x32_bf16(vf, pf, oacc[c], 0, 0, 0); }
;             }
;             bf16* op = O + qrow * D + (qrow >> 8) * adjo + qh * 64 + 4 * fq;
; #pragma unroll
;             for (int c = 0; c < 4; ++c) { u32x2 w; w.x = pk2(oacc[c][0] * rl, oacc[c][1] * rl); w.y = pk2(oacc[c][2] * rl, oacc[c][3] * rl); *(u32x2*)(op + 16 * c) = w; }
	v_mfma_f32_16x16x32_bf16 v[78:81], v[138:141], v[94:97], v[78:81]
	v_cvt_pk_bf16_f32 v97, v154, v155
	v_or_b32_e32 v94, s48, v121
	v_mad_u64_u32 v[98:99], s[18:19], v94, s42, v[110:111]
	v_cvt_pk_bf16_f32 v96, v152, v153
	ds_read_b64_tr_b16 v[128:129], v98 offset:41472
	ds_read_b64_tr_b16 v[126:127], v98 offset:39168
	v_cvt_pk_bf16_f32 v95, v150, v151
	v_cvt_pk_bf16_f32 v94, v148, v149
	ds_read_b64_tr_b16 v[132:133], v98 offset:41504
	ds_read_b64_tr_b16 v[130:131], v98 offset:39200
	ds_read_b64_tr_b16 v[134:135], v98 offset:39232
	ds_read_b64_tr_b16 v[138:139], v98 offset:39264
	ds_read_b64_tr_b16 v[136:137], v98 offset:41536
	ds_read_b64_tr_b16 v[140:141], v98 offset:41568
	v_add_f32_e32 v98, v115, v164
	s_waitcnt lgkmcnt(6)
	v_mfma_f32_16x16x32_bf16 v[82:85], v[126:129], v[94:97], v[82:85]
	v_add_f32_e32 v98, v113, v98
	v_add_f32_e32 v144, v125, v98
	v_sub_f32_e32 v98, v146, v76
	s_waitcnt lgkmcnt(4)
	v_mfma_f32_16x16x32_bf16 v[86:89], v[130:133], v[94:97], v[86:89]
	v_mul_f32_e32 v98, 0x3fb8aa3b, v98
	s_waitcnt lgkmcnt(1)
	v_mfma_f32_16x16x32_bf16 v[90:93], v[134:137], v[94:97], v[90:93]
	v_exp_f32_e32 v145, v98
	s_waitcnt lgkmcnt(0)
	v_mfma_f32_16x16x32_bf16 v[78:81], v[138:141], v[94:97], v[78:81]
	v_cvt_pk_bf16_f32 v97, v162, v163
	v_or_b32_e32 v94, s47, v121
	v_mad_u64_u32 v[98:99], s[18:19], v94, s42, v[110:111]
	v_cvt_pk_bf16_f32 v96, v160, v161
	ds_read_b64_tr_b16 v[128:129], v98 offset:41472
	ds_read_b64_tr_b16 v[126:127], v98 offset:39168
	v_cvt_pk_bf16_f32 v95, v158, v159
	v_cvt_pk_bf16_f32 v94, v156, v157
	ds_read_b64_tr_b16 v[132:133], v98 offset:41504
	ds_read_b64_tr_b16 v[130:131], v98 offset:39200
	ds_read_b64_tr_b16 v[134:135], v98 offset:39232
	ds_read_b64_tr_b16 v[138:139], v98 offset:39264
	ds_read_b64_tr_b16 v[136:137], v98 offset:41536
	ds_read_b64_tr_b16 v[140:141], v98 offset:41568
	v_sub_f32_e32 v98, v147, v76
	v_mul_f32_e32 v98, 0x3fb8aa3b, v98
	v_exp_f32_e32 v98, v98
	v_add_f32_e32 v99, v77, v144
	v_add_f32_e32 v99, v145, v99
	s_waitcnt lgkmcnt(6)
	v_mfma_f32_16x16x32_bf16 v[82:85], v[126:129], v[94:97], v[82:85]
	v_add_f32_e32 v99, v98, v99
	ds_bpermute_b32 v126, v111, v99
	v_sub_f32_e32 v76, v117, v76
	s_waitcnt lgkmcnt(5)
	v_mfma_f32_16x16x32_bf16 v[86:89], v[130:133], v[94:97], v[86:89]
	v_mul_f32_e32 v76, 0x3fb8aa3b, v76
	v_exp_f32_e32 v76, v76
	s_waitcnt lgkmcnt(0)
	v_add_f32_e32 v144, v99, v126
	v_mfma_f32_16x16x32_bf16 v[90:93], v[134:137], v[94:97], v[90:93]
	v_mfma_f32_16x16x32_bf16 v[78:81], v[138:141], v[94:97], v[78:81]
	v_bfe_u32 v96, v113, 16, 1
	v_add3_u32 v113, v113, v96, s39
	v_bfe_u32 v96, v115, 16, 1
	v_bfe_u32 v94, v98, 16, 1
	v_add3_u32 v96, v115, v96, s39
	v_add3_u32 v94, v98, v94, s39
	v_bfe_u32 v98, v145, 16, 1
	v_lshrrev_b32_e32 v95, 16, v96
	v_add3_u32 v98, v145, v98, s39
	v_cvt_pk_bf16_f32 v96, v125, v77
	v_or_b32_e32 v77, s46, v121
	v_lshrrev_b32_e32 v97, 16, v98
	v_mad_u64_u32 v[98:99], s[18:19], v77, s42, v[110:111]
	ds_bpermute_b32 v77, v120, v144
	v_and_or_b32 v95, v113, s38, v95
	v_and_or_b32 v97, v94, s38, v97
	ds_read_b64_tr_b16 v[128:129], v98 offset:41472
	ds_read_b64_tr_b16 v[126:127], v98 offset:39168
	v_cvt_pk_bf16_f32 v94, v142, v143
	s_waitcnt lgkmcnt(2)
	v_add_f32_e32 v77, v144, v77
	v_add_f32_e32 v113, v76, v77
	ds_read_b64_tr_b16 v[132:133], v98 offset:41504
	ds_read_b64_tr_b16 v[130:131], v98 offset:39200
	ds_read_b64_tr_b16 v[134:135], v98 offset:39232
	ds_read_b64_tr_b16 v[138:139], v98 offset:39264
	ds_read_b64_tr_b16 v[136:137], v98 offset:41536
	ds_read_b64_tr_b16 v[140:141], v98 offset:41568
	v_div_scale_f32 v115, s[18:19], v113, v113, 1.0
	v_rcp_f32_e32 v125, v115
	s_waitcnt lgkmcnt(0)
	v_mfma_f32_16x16x32_bf16 v[76:79], v[138:141], v[94:97], v[78:81]
	v_lshl_add_u64 v[98:99], v[44:45], 0, s[28:29]
	s_nop 1
	v_fma_f32 v80, -v115, v125, 1.0
	v_fmac_f32_e32 v125, v80, v125
	v_div_scale_f32 v80, vcc, 1.0, v113, 1.0
	v_mul_f32_e32 v81, v80, v125
	v_mfma_f32_16x16x32_bf16 v[82:85], v[126:129], v[94:97], v[82:85]
	v_mfma_f32_16x16x32_bf16 v[86:89], v[130:133], v[94:97], v[86:89]
	v_mfma_f32_16x16x32_bf16 v[90:93], v[134:137], v[94:97], v[90:93]
	v_fma_f32 v94, -v115, v81, v80
	v_fmac_f32_e32 v81, v94, v125
	v_fma_f32 v80, -v115, v81, v80
	v_div_fmas_f32 v80, v80, v125, v81
	v_div_fixup_f32 v80, v80, v113, 1.0
	s_nop 0
	v_mov_b32_e32 v96, v82
	v_mov_b32_e32 v97, v84
	v_pk_mul_f32 v[96:97], v[96:97], v[80:81] op_sel_hi:[1,0]
	v_mov_b32_e32 v84, v83
	v_pk_mul_f32 v[82:83], v[84:85], v[80:81] op_sel_hi:[1,0]
	v_lshlrev_b64 v[94:95], 12, v[98:99]
	v_cvt_pk_bf16_f32 v82, v96, v82
	v_cvt_pk_bf16_f32 v83, v97, v83
	v_lshl_add_u64 v[94:95], v[118:119], 0, v[94:95]
	global_store_dwordx2 v[94:95], v[82:83], off
	v_mov_b32_e32 v82, v86
	v_mov_b32_e32 v83, v88
	v_pk_mul_f32 v[82:83], v[80:81], v[82:83] op_sel_hi:[0,1]
	v_mov_b32_e32 v88, v87
	v_pk_mul_f32 v[84:85], v[80:81], v[88:89] op_sel_hi:[0,1]
	v_cvt_pk_bf16_f32 v82, v82, v84
	v_cvt_pk_bf16_f32 v83, v83, v85
	global_store_dwordx2 v[94:95], v[82:83], off offset:32
	v_mov_b32_e32 v82, v90
	v_mov_b32_e32 v83, v92
	v_pk_mul_f32 v[82:83], v[80:81], v[82:83] op_sel_hi:[0,1]
	v_mov_b32_e32 v92, v91
	v_pk_mul_f32 v[84:85], v[80:81], v[92:93] op_sel_hi:[0,1]
	v_cvt_pk_bf16_f32 v82, v82, v84
	v_cvt_pk_bf16_f32 v83, v83, v85
	global_store_dwordx2 v[94:95], v[82:83], off offset:64
	v_mov_b32_e32 v83, v78
	v_mov_b32_e32 v78, v77
	v_mov_b32_e32 v82, v76
	v_pk_mul_f32 v[76:77], v[80:81], v[78:79] op_sel_hi:[0,1]
	v_pk_mul_f32 v[82:83], v[80:81], v[82:83] op_sel_hi:[0,1]
	v_cvt_pk_bf16_f32 v76, v82, v76
	v_cvt_pk_bf16_f32 v77, v83, v77
	global_store_dwordx2 v[94:95], v[76:77], off offset:96
	v_mov_b64_e32 v[98:99], v[62:63]
	v_mov_b64_e32 v[94:95], v[66:67]
	v_mov_b64_e32 v[90:91], v[70:71]
	v_mov_b64_e32 v[86:87], v[74:75]
	v_mov_b64_e32 v[82:83], v[58:59]
	v_mov_b64_e32 v[78:79], v[54:55]
	v_mov_b64_e32 v[96:97], v[60:61]
	v_mov_b64_e32 v[92:93], v[64:65]
	v_mov_b64_e32 v[88:89], v[68:69]
	v_mov_b64_e32 v[84:85], v[72:73]
	v_mov_b64_e32 v[80:81], v[56:57]
	v_mov_b64_e32 v[76:77], v[52:53]
	s_cbranch_scc1 .LBB0_1740
